# LDS-DMA staging loads in scalar-base form (SGPR base + 32-bit lane offset) in GEMM main loops
# speedup vs baseline: 1.0033x; 1.0033x over previous
; #define PG8_STAGE(bufoff, gbase, voff) do { _Pragma("unroll") for (int _i = 0; _i < 2; ++_i) \
;         __builtin_amdgcn_global_load_lds((const unsigned*)((const char*)(gbase) + (voff)[_i]), (PG8_LAS unsigned*)(lds + (bufoff) + ldsw + _i * 8192), 16, 0, 0); } while (0)
; #define PG8_LDA(dst, b, h) do { _Pragma("unroll") for (int m = 0; m < 4; ++m) _Pragma("unroll") for (int k = 0; k < 2; ++k) dst[m][k] = *(const PG8_LAS bf16x8*)(lds + PG8_SA(b, h) + aoff + m * 2048 + k * 1024); } while (0)
; #define PG8_LDB(dst, b, h) do { _Pragma("unroll") for (int n = 0; n < 2; ++n) _Pragma("unroll") for (int k = 0; k < 2; ++k) dst[n][k] = *(const PG8_LAS bf16x8*)(lds + PG8_SB(b, h) + boff + n * 2048 + k * 1024); } while (0)
; #define PG8_MMA(ai, bj, At, Bt) do { __builtin_amdgcn_s_setprio(1); _Pragma("unroll") for (int m = 0; m < 4; ++m) _Pragma("unroll") for (int n = 0; n < 2; ++n) _Pragma("unroll") for (int k = 0; k < 2; ++k) \
;         acc[ai][bj][m][n] = __builtin_amdgcn_mfma_f32_16x16x32_bf16(Bt[n][k], At[m][k], acc[ai][bj][m][n], 0, 0, 0); __builtin_amdgcn_s_setprio(0); } while (0)
; #define PG8_WAIT_V(n) asm volatile("s_waitcnt vmcnt(" #n ")" ::: "memory")
; #define PG8_WAIT_L(n) asm volatile("s_waitcnt lgkmcnt(" #n ")" ::: "memory")
; template <class Epi, class Sched, bool ALIGN_EPI = false, bool SP2 = false>
; __device__ __forceinline__ void gemm_phase(PG8_LAS unsigned char* lds, const Gemm g, const Sched& S, const Epi& E) {
;     ...
;         for (int t = 0; t < nt; t += 2) {
;             const bool last = (t == nt - 2);
;             const char* a1 = cA + (size_t)(t + 1) * kstep;
;             const char* a2 = last ? nA : cA + (size_t)(t + 2) * kstep; const char* b2 = last ? nB : cB + (size_t)(t + 2) * kstep;
;             const char* a3 = a2 + kstep; const char* b3 = b2 + kstep;
;             if (last && has_next) S.a_ready(nxt);
;             if constexpr (Epi::MID) { if (t == nt / 2) E.mid(acc, cur, wr, wc, fr, fq); }
;             if constexpr (SP2) {
;             PG8_LDB(B0, 0, 0); PG8_LDB(B1, 0, 1); PG8_SCHED; PG8_LDA(At, 0, 0); PG8_STAGE(PG8_SA(1, 1), a1 + hstep, voffA);
;             PG8_WAIT_V(8); PG8_WAIT_L(0); PG8_BAR; PG8_MMA(0, 0, At, B0); PG8_MMA(0, 1, At, B1); PG8_BAR; PG8_SCHED;
;             PG8_LDA(At, 0, 1); PG8_STAGE(PG8_SB(0, 0), b2, voffB); PG8_STAGE(PG8_SB(0, 1), b2 + hstep, voffB); PG8_STAGE(PG8_SA(0, 0), a2, voffA);
.LBB0_373:
	s_add_u32 s28, s26, 0xfff80080
	s_addc_u32 s29, s27, -1
	s_add_i32 s33, 0, 0x10000
	s_cmp_eq_u32 s55, 28
	s_cselect_b32 s31, s5, s29
	s_cselect_b32 s30, s11, s28
	v_add_u32_e32 v161, s33, v155
	s_cselect_b32 s29, s19, s54
	s_cselect_b32 s28, s21, s53
	s_add_i32 s58, 0, 0x14000
	ds_read_b128 v[142:145], v161
	ds_read_b128 v[146:149], v161 offset:1024
	ds_read_b128 v[150:153], v161 offset:2048
	ds_read_b128 v[162:165], v161 offset:3072
	v_add_u32_e32 v161, s58, v155
	ds_read_b128 v[166:169], v161
	ds_read_b128 v[170:173], v161 offset:1024
	ds_read_b128 v[174:177], v161 offset:2048
	ds_read_b128 v[178:181], v161 offset:3072
	v_lshl_add_u64 v[202:203], s[26:27], 0, v[140:141]
	s_add_i32 m0, s41, 0xc000
	ds_read_b128 v[182:185], v160
	ds_read_b128 v[186:189], v160 offset:1024
	ds_read_b128 v[190:193], v160 offset:2048
	ds_read_b128 v[194:197], v160 offset:3072
	ds_read_b128 v[198:201], v160 offset:4096
	ds_read_b128 v[206:209], v160 offset:5120
	ds_read_b128 v[210:213], v160 offset:6144
	ds_read_b128 v[214:217], v160 offset:7168
	global_load_lds_dwordx4 v140, s[26:27]
	v_lshl_add_u64 v[202:203], s[26:27], 0, v[138:139]
	s_add_i32 m0, s41, 0xe000
	s_nop 0
	global_load_lds_dwordx4 v138, s[26:27]
	s_waitcnt vmcnt(8)
	s_waitcnt lgkmcnt(0)
	s_barrier
	s_setprio 1
	s_waitcnt lgkmcnt(0)
	v_mfma_f32_16x16x32_bf16 v[130:133], v[142:145], v[182:185], v[130:133]
	v_mfma_f32_16x16x32_bf16 v[126:129], v[150:153], v[182:185], v[126:129]
	v_mfma_f32_16x16x32_bf16 v[114:117], v[142:145], v[190:193], v[114:117]
	v_mfma_f32_16x16x32_bf16 v[110:113], v[150:153], v[190:193], v[110:113]
	v_mfma_f32_16x16x32_bf16 v[98:101], v[142:145], v[198:201], v[98:101]
	v_mfma_f32_16x16x32_bf16 v[94:97], v[150:153], v[198:201], v[94:97]
	v_mfma_f32_16x16x32_bf16 v[82:85], v[142:145], v[210:213], v[82:85]
	v_mfma_f32_16x16x32_bf16 v[78:81], v[150:153], v[210:213], v[78:81]
	v_mfma_f32_16x16x32_bf16 v[130:133], v[146:149], v[186:189], v[130:133]
	v_mfma_f32_16x16x32_bf16 v[126:129], v[162:165], v[186:189], v[126:129]
	v_mfma_f32_16x16x32_bf16 v[114:117], v[146:149], v[194:197], v[114:117]
	v_mfma_f32_16x16x32_bf16 v[110:113], v[162:165], v[194:197], v[110:113]
	v_mfma_f32_16x16x32_bf16 v[98:101], v[146:149], v[206:209], v[98:101]
	v_mfma_f32_16x16x32_bf16 v[94:97], v[162:165], v[206:209], v[94:97]
	v_mfma_f32_16x16x32_bf16 v[82:85], v[146:149], v[214:217], v[82:85]
	v_mfma_f32_16x16x32_bf16 v[78:81], v[162:165], v[214:217], v[78:81]
	s_setprio 0
	s_setprio 1
	v_mfma_f32_16x16x32_bf16 v[122:125], v[166:169], v[182:185], v[122:125]
	v_mfma_f32_16x16x32_bf16 v[118:121], v[174:177], v[182:185], v[118:121]
	v_mfma_f32_16x16x32_bf16 v[106:109], v[166:169], v[190:193], v[106:109]
	v_mfma_f32_16x16x32_bf16 v[102:105], v[174:177], v[190:193], v[102:105]
	v_mfma_f32_16x16x32_bf16 v[90:93], v[166:169], v[198:201], v[90:93]
	v_mfma_f32_16x16x32_bf16 v[86:89], v[174:177], v[198:201], v[86:89]
	v_mfma_f32_16x16x32_bf16 v[74:77], v[166:169], v[210:213], v[74:77]
	v_mfma_f32_16x16x32_bf16 v[70:73], v[174:177], v[210:213], v[70:73]
	v_mfma_f32_16x16x32_bf16 v[122:125], v[170:173], v[186:189], v[122:125]
	v_mfma_f32_16x16x32_bf16 v[118:121], v[178:181], v[186:189], v[118:121]
	v_mfma_f32_16x16x32_bf16 v[106:109], v[170:173], v[194:197], v[106:109]
	v_mfma_f32_16x16x32_bf16 v[102:105], v[178:181], v[194:197], v[102:105]
	v_mfma_f32_16x16x32_bf16 v[90:93], v[170:173], v[206:209], v[90:93]
	v_mfma_f32_16x16x32_bf16 v[86:89], v[178:181], v[206:209], v[86:89]
	v_mfma_f32_16x16x32_bf16 v[74:77], v[170:173], v[214:217], v[74:77]
	v_mfma_f32_16x16x32_bf16 v[70:73], v[178:181], v[214:217], v[70:73]
	s_setprio 0
	s_barrier
	s_add_i32 s33, s33, s39
	v_lshl_add_u64 v[202:203], s[28:29], 0, v[0:1]
	s_mov_b32 m0, s33
	ds_read_b128 v[182:185], v160 offset:16384
	ds_read_b128 v[186:189], v160 offset:17408
	ds_read_b128 v[190:193], v160 offset:18432
	ds_read_b128 v[194:197], v160 offset:19456
	ds_read_b128 v[198:201], v160 offset:20480
	ds_read_b128 v[206:209], v160 offset:21504
	ds_read_b128 v[210:213], v160 offset:22528
	ds_read_b128 v[214:217], v160 offset:23552
	global_load_lds_dwordx4 v0, s[28:29]
	s_add_i32 m0, s33, 0x2000
	s_add_u32 s56, s28, 0x80000
	v_lshl_add_u64 v[218:219], s[28:29], 0, v[14:15]
	s_addc_u32 s57, s29, 0
	s_add_i32 s33, s58, s39
	global_load_lds_dwordx4 v14, s[28:29]
	v_lshl_add_u64 v[220:221], s[56:57], 0, v[0:1]
	s_mov_b32 m0, s33
	v_lshl_add_u64 v[222:223], s[30:31], 0, v[134:135]
	global_load_lds_dwordx4 v0, s[56:57]
	v_lshl_add_u64 v[220:221], s[56:57], 0, v[14:15]
	s_add_i32 m0, s33, 0x2000
	s_nop 0
	global_load_lds_dwordx4 v14, s[56:57]
	v_lshl_add_u64 v[220:221], s[30:31], 0, v[136:137]
	s_mov_b32 m0, s41
	s_nop 0
	global_load_lds_dwordx4 v136, s[30:31]
	s_mov_b32 m0, s42
	s_nop 0
	global_load_lds_dwordx4 v134, s[30:31]
	s_waitcnt vmcnt(8)
	s_waitcnt lgkmcnt(0)
	s_barrier
; #define PG8_STAGE(bufoff, gbase, voff) do { _Pragma("unroll") for (int _i = 0; _i < 2; ++_i) \
;         __builtin_amdgcn_global_load_lds((const unsigned*)((const char*)(gbase) + (voff)[_i]), (PG8_LAS unsigned*)(lds + (bufoff) + ldsw + _i * 8192), 16, 0, 0); } while (0)
; #define PG8_LDA(dst, b, h) do { _Pragma("unroll") for (int m = 0; m < 4; ++m) _Pragma("unroll") for (int k = 0; k < 2; ++k) dst[m][k] = *(const PG8_LAS bf16x8*)(lds + PG8_SA(b, h) + aoff + m * 2048 + k * 1024); } while (0)
; #define PG8_LDB(dst, b, h) do { _Pragma("unroll") for (int n = 0; n < 2; ++n) _Pragma("unroll") for (int k = 0; k < 2; ++k) dst[n][k] = *(const PG8_LAS bf16x8*)(lds + PG8_SB(b, h) + boff + n * 2048 + k * 1024); } while (0)
; #define PG8_MMA(ai, bj, At, Bt) do { __builtin_amdgcn_s_setprio(1); _Pragma("unroll") for (int m = 0; m < 4; ++m) _Pragma("unroll") for (int n = 0; n < 2; ++n) _Pragma("unroll") for (int k = 0; k < 2; ++k) \
;         acc[ai][bj][m][n] = __builtin_amdgcn_mfma_f32_16x16x32_bf16(Bt[n][k], At[m][k], acc[ai][bj][m][n], 0, 0, 0); __builtin_amdgcn_s_setprio(0); } while (0)
; #define PG8_WAIT_V(n) asm volatile("s_waitcnt vmcnt(" #n ")" ::: "memory")
; #define PG8_WAIT_L(n) asm volatile("s_waitcnt lgkmcnt(" #n ")" ::: "memory")
; #define PG8_BAR __builtin_amdgcn_s_barrier()
; #define PG8_SCHED __builtin_amdgcn_sched_barrier(0)
; template <class Epi, class Sched, bool ALIGN_EPI = false, bool SP2 = false>
; __device__ __forceinline__ void gemm_phase(PG8_LAS unsigned char* lds, const Gemm g, const Sched& S, const Epi& E) {
;     ...
;             PG8_WAIT_V(8); PG8_WAIT_L(0); PG8_BAR; PG8_MMA(1, 0, At, B0); PG8_MMA(1, 1, At, B1); PG8_BAR; PG8_SCHED;
;             PG8_LDB(B0, 1, 0); PG8_LDB(B1, 1, 1); PG8_SCHED; PG8_LDA(At, 1, 0); PG8_STAGE(PG8_SA(0, 1), a2 + hstep, voffA);
;             PG8_WAIT_V(8); PG8_WAIT_L(0); PG8_BAR; PG8_MMA(0, 0, At, B0); PG8_MMA(0, 1, At, B1); PG8_BAR; PG8_SCHED;
	s_setprio 1
	s_waitcnt lgkmcnt(0)
	v_mfma_f32_16x16x32_bf16 v[66:69], v[142:145], v[182:185], v[66:69]
	v_mfma_f32_16x16x32_bf16 v[62:65], v[150:153], v[182:185], v[62:65]
	v_mfma_f32_16x16x32_bf16 v[50:53], v[142:145], v[190:193], v[50:53]
	v_mfma_f32_16x16x32_bf16 v[46:49], v[150:153], v[190:193], v[46:49]
	v_mfma_f32_16x16x32_bf16 v[34:37], v[142:145], v[198:201], v[34:37]
	v_mfma_f32_16x16x32_bf16 v[30:33], v[150:153], v[198:201], v[30:33]
	v_mfma_f32_16x16x32_bf16 v[18:21], v[142:145], v[210:213], v[18:21]
	v_mfma_f32_16x16x32_bf16 v[10:13], v[150:153], v[210:213], v[10:13]
	v_mfma_f32_16x16x32_bf16 v[66:69], v[146:149], v[186:189], v[66:69]
	v_mfma_f32_16x16x32_bf16 v[62:65], v[162:165], v[186:189], v[62:65]
	v_mfma_f32_16x16x32_bf16 v[50:53], v[146:149], v[194:197], v[50:53]
	v_mfma_f32_16x16x32_bf16 v[46:49], v[162:165], v[194:197], v[46:49]
	v_mfma_f32_16x16x32_bf16 v[34:37], v[146:149], v[206:209], v[34:37]
	v_mfma_f32_16x16x32_bf16 v[30:33], v[162:165], v[206:209], v[30:33]
	v_mfma_f32_16x16x32_bf16 v[18:21], v[146:149], v[214:217], v[18:21]
	v_mfma_f32_16x16x32_bf16 v[10:13], v[162:165], v[214:217], v[10:13]
	s_setprio 0
	s_setprio 1
	v_mfma_f32_16x16x32_bf16 v[58:61], v[166:169], v[182:185], v[58:61]
	v_mfma_f32_16x16x32_bf16 v[54:57], v[174:177], v[182:185], v[54:57]
	v_mfma_f32_16x16x32_bf16 v[42:45], v[166:169], v[190:193], v[42:45]
	v_mfma_f32_16x16x32_bf16 v[38:41], v[174:177], v[190:193], v[38:41]
	v_mfma_f32_16x16x32_bf16 v[26:29], v[166:169], v[198:201], v[26:29]
	v_mfma_f32_16x16x32_bf16 v[22:25], v[174:177], v[198:201], v[22:25]
	v_mfma_f32_16x16x32_bf16 v[6:9], v[166:169], v[210:213], v[6:9]
	v_mfma_f32_16x16x32_bf16 v[2:5], v[174:177], v[210:213], v[2:5]
	v_mfma_f32_16x16x32_bf16 v[58:61], v[170:173], v[186:189], v[58:61]
	v_mfma_f32_16x16x32_bf16 v[54:57], v[178:181], v[186:189], v[54:57]
	v_mfma_f32_16x16x32_bf16 v[42:45], v[170:173], v[194:197], v[42:45]
	v_mfma_f32_16x16x32_bf16 v[38:41], v[178:181], v[194:197], v[38:41]
	v_mfma_f32_16x16x32_bf16 v[26:29], v[170:173], v[206:209], v[26:29]
	v_mfma_f32_16x16x32_bf16 v[22:25], v[178:181], v[206:209], v[22:25]
	v_mfma_f32_16x16x32_bf16 v[6:9], v[170:173], v[214:217], v[6:9]
	v_mfma_f32_16x16x32_bf16 v[2:5], v[178:181], v[214:217], v[2:5]
	s_setprio 0
	s_barrier
	s_add_i32 s33, 0, 0x18000
	v_add_u32_e32 v161, s33, v155
	s_add_i32 s56, 0, 0x1c000
	ds_read_b128 v[142:145], v161
	ds_read_b128 v[146:149], v161 offset:1024
	ds_read_b128 v[150:153], v161 offset:2048
	ds_read_b128 v[162:165], v161 offset:3072
	v_add_u32_e32 v161, s56, v155
	ds_read_b128 v[166:169], v161
	ds_read_b128 v[170:173], v161 offset:1024
	ds_read_b128 v[174:177], v161 offset:2048
	ds_read_b128 v[178:181], v161 offset:3072
	s_add_u32 s30, s30, 0x80000
	s_addc_u32 s31, s31, 0
	s_mov_b32 m0, s43
	v_lshl_add_u64 v[224:225], s[30:31], 0, v[136:137]
	ds_read_b128 v[182:185], v160 offset:32768
	ds_read_b128 v[186:189], v160 offset:33792
	ds_read_b128 v[190:193], v160 offset:34816
	ds_read_b128 v[194:197], v160 offset:35840
	ds_read_b128 v[198:201], v160 offset:36864
	ds_read_b128 v[206:209], v160 offset:37888
	ds_read_b128 v[210:213], v160 offset:38912
	ds_read_b128 v[214:217], v160 offset:39936
	global_load_lds_dwordx4 v136, s[30:31]
	v_lshl_add_u64 v[224:225], s[30:31], 0, v[134:135]
	s_mov_b32 m0, s44
	s_nop 0
	global_load_lds_dwordx4 v134, s[30:31]
	s_waitcnt vmcnt(8)
	s_waitcnt lgkmcnt(0)
	s_barrier
	s_setprio 1
	s_waitcnt lgkmcnt(0)
	v_mfma_f32_16x16x32_bf16 v[130:133], v[142:145], v[182:185], v[130:133]
	v_mfma_f32_16x16x32_bf16 v[126:129], v[150:153], v[182:185], v[126:129]
	v_mfma_f32_16x16x32_bf16 v[114:117], v[142:145], v[190:193], v[114:117]
	v_mfma_f32_16x16x32_bf16 v[110:113], v[150:153], v[190:193], v[110:113]
	v_mfma_f32_16x16x32_bf16 v[98:101], v[142:145], v[198:201], v[98:101]
	v_mfma_f32_16x16x32_bf16 v[94:97], v[150:153], v[198:201], v[94:97]
	v_mfma_f32_16x16x32_bf16 v[82:85], v[142:145], v[210:213], v[82:85]
	v_mfma_f32_16x16x32_bf16 v[78:81], v[150:153], v[210:213], v[78:81]
	v_mfma_f32_16x16x32_bf16 v[130:133], v[146:149], v[186:189], v[130:133]
	v_mfma_f32_16x16x32_bf16 v[126:129], v[162:165], v[186:189], v[126:129]
	v_mfma_f32_16x16x32_bf16 v[114:117], v[146:149], v[194:197], v[114:117]
	v_mfma_f32_16x16x32_bf16 v[110:113], v[162:165], v[194:197], v[110:113]
	v_mfma_f32_16x16x32_bf16 v[98:101], v[146:149], v[206:209], v[98:101]
	v_mfma_f32_16x16x32_bf16 v[94:97], v[162:165], v[206:209], v[94:97]
	v_mfma_f32_16x16x32_bf16 v[82:85], v[146:149], v[214:217], v[82:85]
	v_mfma_f32_16x16x32_bf16 v[78:81], v[162:165], v[214:217], v[78:81]
	s_setprio 0
	s_setprio 1
	v_mfma_f32_16x16x32_bf16 v[122:125], v[166:169], v[182:185], v[122:125]
	v_mfma_f32_16x16x32_bf16 v[118:121], v[174:177], v[182:185], v[118:121]
	v_mfma_f32_16x16x32_bf16 v[106:109], v[166:169], v[190:193], v[106:109]
	v_mfma_f32_16x16x32_bf16 v[102:105], v[174:177], v[190:193], v[102:105]
	v_mfma_f32_16x16x32_bf16 v[90:93], v[166:169], v[198:201], v[90:93]
	v_mfma_f32_16x16x32_bf16 v[86:89], v[174:177], v[198:201], v[86:89]
	v_mfma_f32_16x16x32_bf16 v[74:77], v[166:169], v[210:213], v[74:77]
	v_mfma_f32_16x16x32_bf16 v[70:73], v[174:177], v[210:213], v[70:73]
	v_mfma_f32_16x16x32_bf16 v[122:125], v[170:173], v[186:189], v[122:125]
	v_mfma_f32_16x16x32_bf16 v[118:121], v[178:181], v[186:189], v[118:121]
	v_mfma_f32_16x16x32_bf16 v[106:109], v[170:173], v[194:197], v[106:109]
	v_mfma_f32_16x16x32_bf16 v[102:105], v[178:181], v[194:197], v[102:105]
	v_mfma_f32_16x16x32_bf16 v[90:93], v[170:173], v[206:209], v[90:93]
	v_mfma_f32_16x16x32_bf16 v[86:89], v[178:181], v[206:209], v[86:89]
	v_mfma_f32_16x16x32_bf16 v[74:77], v[170:173], v[214:217], v[74:77]
	v_mfma_f32_16x16x32_bf16 v[70:73], v[178:181], v[214:217], v[70:73]
	s_setprio 0
	s_barrier
; #define PG8_STAGE(bufoff, gbase, voff) do { _Pragma("unroll") for (int _i = 0; _i < 2; ++_i) \
;         __builtin_amdgcn_global_load_lds((const unsigned*)((const char*)(gbase) + (voff)[_i]), (PG8_LAS unsigned*)(lds + (bufoff) + ldsw + _i * 8192), 16, 0, 0); } while (0)
; #define PG8_LDA(dst, b, h) do { _Pragma("unroll") for (int m = 0; m < 4; ++m) _Pragma("unroll") for (int k = 0; k < 2; ++k) dst[m][k] = *(const PG8_LAS bf16x8*)(lds + PG8_SA(b, h) + aoff + m * 2048 + k * 1024); } while (0)
; #define PG8_MMA(ai, bj, At, Bt) do { __builtin_amdgcn_s_setprio(1); _Pragma("unroll") for (int m = 0; m < 4; ++m) _Pragma("unroll") for (int n = 0; n < 2; ++n) _Pragma("unroll") for (int k = 0; k < 2; ++k) \
;         acc[ai][bj][m][n] = __builtin_amdgcn_mfma_f32_16x16x32_bf16(Bt[n][k], At[m][k], acc[ai][bj][m][n], 0, 0, 0); __builtin_amdgcn_s_setprio(0); } while (0)
; #define PG8_WAIT_V(n) asm volatile("s_waitcnt vmcnt(" #n ")" ::: "memory")
; #define PG8_WAIT_L(n) asm volatile("s_waitcnt lgkmcnt(" #n ")" ::: "memory")
; #define PG8_BAR __builtin_amdgcn_s_barrier()
; #define PG8_SCHED __builtin_amdgcn_sched_barrier(0)
; template <class Epi, class Sched, bool ALIGN_EPI = false, bool SP2 = false>
; __device__ __forceinline__ void gemm_phase(PG8_LAS unsigned char* lds, const Gemm g, const Sched& S, const Epi& E) {
;     ...
;             PG8_LDA(At, 1, 1); PG8_STAGE(PG8_SB(1, 0), b3, voffB); PG8_STAGE(PG8_SB(1, 1), b3 + hstep, voffB); PG8_STAGE(PG8_SA(1, 0), a3, voffA);
;             PG8_WAIT_V(8); PG8_WAIT_L(0); PG8_BAR; PG8_MMA(1, 0, At, B0); PG8_MMA(1, 1, At, B1); PG8_BAR; PG8_SCHED;
;     ...
;         if constexpr (ALIGN_EPI) { if (wr == 0) PG8_BAR; }
	s_add_i32 s30, s33, s39
	v_lshl_add_u64 v[202:203], v[202:203], 0, s[92:93]
	s_mov_b32 m0, s30
	ds_read_b128 v[182:185], v160 offset:49152
	ds_read_b128 v[186:189], v160 offset:50176
	ds_read_b128 v[190:193], v160 offset:51200
	ds_read_b128 v[194:197], v160 offset:52224
	ds_read_b128 v[198:201], v160 offset:53248
	ds_read_b128 v[206:209], v160 offset:54272
	ds_read_b128 v[210:213], v160 offset:55296
	ds_read_b128 v[214:217], v160 offset:56320
	global_load_lds_dwordx4 v[202:203], off
	s_add_i32 m0, s30, 0x2000
	s_add_u32 s28, s28, 0x80080
	v_lshl_add_u64 v[202:203], v[218:219], 0, s[92:93]
	s_addc_u32 s29, s29, 0
	s_add_i32 s30, s56, s39
	global_load_lds_dwordx4 v[202:203], off
	v_lshl_add_u64 v[202:203], s[28:29], 0, v[0:1]
	s_mov_b32 m0, s30
	s_nop 0
	global_load_lds_dwordx4 v0, s[28:29]
	v_lshl_add_u64 v[202:203], s[28:29], 0, v[14:15]
	s_add_i32 m0, s30, 0x2000
	s_nop 0
	global_load_lds_dwordx4 v14, s[28:29]
	v_lshl_add_u64 v[202:203], v[220:221], 0, s[92:93]
	s_mov_b32 m0, s46
	s_nop 0
	global_load_lds_dwordx4 v[202:203], off
	v_lshl_add_u64 v[202:203], v[222:223], 0, s[92:93]
	s_mov_b32 m0, s47
	s_nop 0
	global_load_lds_dwordx4 v[202:203], off
	s_waitcnt vmcnt(8)
	s_waitcnt lgkmcnt(0)
	s_barrier
	s_setprio 1
	s_waitcnt lgkmcnt(0)
	v_mfma_f32_16x16x32_bf16 v[66:69], v[142:145], v[182:185], v[66:69]
	v_mfma_f32_16x16x32_bf16 v[62:65], v[150:153], v[182:185], v[62:65]
	v_mfma_f32_16x16x32_bf16 v[50:53], v[142:145], v[190:193], v[50:53]
	v_mfma_f32_16x16x32_bf16 v[46:49], v[150:153], v[190:193], v[46:49]
	v_mfma_f32_16x16x32_bf16 v[34:37], v[142:145], v[198:201], v[34:37]
	v_mfma_f32_16x16x32_bf16 v[30:33], v[150:153], v[198:201], v[30:33]
	v_mfma_f32_16x16x32_bf16 v[18:21], v[142:145], v[210:213], v[18:21]
	v_mfma_f32_16x16x32_bf16 v[10:13], v[150:153], v[210:213], v[10:13]
	v_mfma_f32_16x16x32_bf16 v[66:69], v[146:149], v[186:189], v[66:69]
	v_mfma_f32_16x16x32_bf16 v[62:65], v[162:165], v[186:189], v[62:65]
	v_mfma_f32_16x16x32_bf16 v[50:53], v[146:149], v[194:197], v[50:53]
	v_mfma_f32_16x16x32_bf16 v[46:49], v[162:165], v[194:197], v[46:49]
	v_mfma_f32_16x16x32_bf16 v[34:37], v[146:149], v[206:209], v[34:37]
	v_mfma_f32_16x16x32_bf16 v[30:33], v[162:165], v[206:209], v[30:33]
	v_mfma_f32_16x16x32_bf16 v[18:21], v[146:149], v[214:217], v[18:21]
	v_mfma_f32_16x16x32_bf16 v[10:13], v[162:165], v[214:217], v[10:13]
	s_setprio 0
	s_setprio 1
	v_mfma_f32_16x16x32_bf16 v[58:61], v[166:169], v[182:185], v[58:61]
	v_mfma_f32_16x16x32_bf16 v[54:57], v[174:177], v[182:185], v[54:57]
	v_mfma_f32_16x16x32_bf16 v[42:45], v[166:169], v[190:193], v[42:45]
	v_mfma_f32_16x16x32_bf16 v[38:41], v[174:177], v[190:193], v[38:41]
	v_mfma_f32_16x16x32_bf16 v[26:29], v[166:169], v[198:201], v[26:29]
	v_mfma_f32_16x16x32_bf16 v[22:25], v[174:177], v[198:201], v[22:25]
	v_mfma_f32_16x16x32_bf16 v[6:9], v[166:169], v[210:213], v[6:9]
	v_mfma_f32_16x16x32_bf16 v[2:5], v[174:177], v[210:213], v[2:5]
	v_mfma_f32_16x16x32_bf16 v[58:61], v[170:173], v[186:189], v[58:61]
	v_mfma_f32_16x16x32_bf16 v[54:57], v[178:181], v[186:189], v[54:57]
	v_mfma_f32_16x16x32_bf16 v[42:45], v[170:173], v[194:197], v[42:45]
	v_mfma_f32_16x16x32_bf16 v[38:41], v[178:181], v[194:197], v[38:41]
	v_mfma_f32_16x16x32_bf16 v[26:29], v[170:173], v[206:209], v[26:29]
	v_mfma_f32_16x16x32_bf16 v[22:25], v[178:181], v[206:209], v[22:25]
	v_mfma_f32_16x16x32_bf16 v[6:9], v[170:173], v[214:217], v[6:9]
	v_mfma_f32_16x16x32_bf16 v[2:5], v[178:181], v[214:217], v[2:5]
	s_setprio 0
	s_barrier
	s_add_i32 s55, s55, 2
	s_add_u32 s53, s53, 0x100
	s_addc_u32 s54, s54, 0
	s_add_u32 s26, s26, 0x100
	s_addc_u32 s27, s27, 0
	s_cmp_gt_u32 s55, 29
	s_cbranch_scc0 .LBB0_373
	s_and_b64 vcc, exec, s[14:15]
	s_cbranch_vccz .LBB0_376
	s_barrier

; #define PG8_STAGE(bufoff, gbase, voff) do { _Pragma("unroll") for (int _i = 0; _i < 2; ++_i) \
;         __builtin_amdgcn_global_load_lds((const unsigned*)((const char*)(gbase) + (voff)[_i]), (PG8_LAS unsigned*)(lds + (bufoff) + ldsw + _i * 8192), 16, 0, 0); } while (0)
; #define PG8_LDA(dst, b, h) do { _Pragma("unroll") for (int m = 0; m < 4; ++m) _Pragma("unroll") for (int k = 0; k < 2; ++k) dst[m][k] = *(const PG8_LAS bf16x8*)(lds + PG8_SA(b, h) + aoff + m * 2048 + k * 1024); } while (0)
; #define PG8_LDB(dst, b, h) do { _Pragma("unroll") for (int n = 0; n < 2; ++n) _Pragma("unroll") for (int k = 0; k < 2; ++k) dst[n][k] = *(const PG8_LAS bf16x8*)(lds + PG8_SB(b, h) + boff + n * 2048 + k * 1024); } while (0)
; #define PG8_MMA(ai, bj, At, Bt) do { __builtin_amdgcn_s_setprio(1); _Pragma("unroll") for (int m = 0; m < 4; ++m) _Pragma("unroll") for (int n = 0; n < 2; ++n) _Pragma("unroll") for (int k = 0; k < 2; ++k) \
;         acc[ai][bj][m][n] = __builtin_amdgcn_mfma_f32_16x16x32_bf16(Bt[n][k], At[m][k], acc[ai][bj][m][n], 0, 0, 0); __builtin_amdgcn_s_setprio(0); } while (0)
; #define PG8_WAIT_V(n) asm volatile("s_waitcnt vmcnt(" #n ")" ::: "memory")
; #define PG8_WAIT_L(n) asm volatile("s_waitcnt lgkmcnt(" #n ")" ::: "memory")
; template <class Epi, class Sched, bool ALIGN_EPI = false, bool SP2 = false>
; __device__ __forceinline__ void gemm_phase(PG8_LAS unsigned char* lds, const Gemm g, const Sched& S, const Epi& E) {
;     ...
;         for (int t = 0; t < nt; t += 2) {
;             const bool last = (t == nt - 2);
;             const char* a1 = cA + (size_t)(t + 1) * kstep;
;             const char* a2 = last ? nA : cA + (size_t)(t + 2) * kstep; const char* b2 = last ? nB : cB + (size_t)(t + 2) * kstep;
;             const char* a3 = a2 + kstep; const char* b3 = b2 + kstep;
;             if (last && has_next) S.a_ready(nxt);
;             if constexpr (Epi::MID) { if (t == nt / 2) E.mid(acc, cur, wr, wc, fr, fq); }
;             if constexpr (SP2) {
;             PG8_LDB(B0, 0, 0); PG8_LDB(B1, 0, 1); PG8_SCHED; PG8_LDA(At, 0, 0); PG8_STAGE(PG8_SA(1, 1), a1 + hstep, voffA);
;             PG8_WAIT_V(8); PG8_WAIT_L(0); PG8_BAR; PG8_MMA(0, 0, At, B0); PG8_MMA(0, 1, At, B1); PG8_BAR; PG8_SCHED;
;             PG8_LDA(At, 0, 1); PG8_STAGE(PG8_SB(0, 0), b2, voffB); PG8_STAGE(PG8_SB(0, 1), b2 + hstep, voffB); PG8_STAGE(PG8_SA(0, 0), a2, voffA);
.LBB0_482:
	s_add_u32 s22, s20, 0x100
	s_addc_u32 s23, s21, 0
	s_add_i32 s33, 0, 0x10000
	s_cmpk_eq_i32 s52, 0x54
	s_cselect_b32 s27, s5, s23
	s_cselect_b32 s26, s4, s22
	s_cselect_b32 s25, s19, s51
	s_cselect_b32 s24, s18, s50
	s_add_i32 s53, 0, 0x14000
	v_add_u32_e32 v138, s33, v199
	v_add_u32_e32 v162, s53, v199
	ds_read_b128 v[118:121], v138
	ds_read_b128 v[130:133], v138 offset:1024
	ds_read_b128 v[134:137], v138 offset:2048
	ds_read_b128 v[138:141], v138 offset:3072
	ds_read_b128 v[146:149], v162
	ds_read_b128 v[154:157], v162 offset:1024
	ds_read_b128 v[158:161], v162 offset:2048
	ds_read_b128 v[162:165], v162 offset:3072
	v_lshl_add_u64 v[202:203], s[20:21], 0, v[212:213]
	s_add_i32 m0, s37, 0xc000
	ds_read_b128 v[166:169], v201
	ds_read_b128 v[170:173], v201 offset:1024
	ds_read_b128 v[174:177], v201 offset:2048
	ds_read_b128 v[178:181], v201 offset:3072
	ds_read_b128 v[182:185], v201 offset:4096
	ds_read_b128 v[186:189], v201 offset:5120
	ds_read_b128 v[190:193], v201 offset:6144
	ds_read_b128 v[194:197], v201 offset:7168
	global_load_lds_dwordx4 v212, s[20:21]
	v_lshl_add_u64 v[202:203], s[20:21], 0, v[210:211]
	s_add_i32 m0, s37, 0xe000
	s_nop 0
	global_load_lds_dwordx4 v210, s[20:21]
	s_waitcnt vmcnt(8)
	s_waitcnt lgkmcnt(0)
	s_barrier
	s_setprio 1
	s_waitcnt lgkmcnt(0)
	v_mfma_f32_16x16x32_bf16 v[150:153], v[118:121], v[166:169], v[150:153]
	v_mfma_f32_16x16x32_bf16 v[142:145], v[134:137], v[166:169], v[142:145]
	v_mfma_f32_16x16x32_bf16 v[114:117], v[118:121], v[174:177], v[114:117]
	v_mfma_f32_16x16x32_bf16 v[110:113], v[134:137], v[174:177], v[110:113]
	v_mfma_f32_16x16x32_bf16 v[98:101], v[118:121], v[182:185], v[98:101]
	v_mfma_f32_16x16x32_bf16 v[94:97], v[134:137], v[182:185], v[94:97]
	v_mfma_f32_16x16x32_bf16 v[82:85], v[118:121], v[190:193], v[82:85]
	v_mfma_f32_16x16x32_bf16 v[78:81], v[134:137], v[190:193], v[78:81]
	v_mfma_f32_16x16x32_bf16 v[150:153], v[130:133], v[170:173], v[150:153]
	v_mfma_f32_16x16x32_bf16 v[142:145], v[138:141], v[170:173], v[142:145]
	v_mfma_f32_16x16x32_bf16 v[114:117], v[130:133], v[178:181], v[114:117]
	v_mfma_f32_16x16x32_bf16 v[110:113], v[138:141], v[178:181], v[110:113]
	v_mfma_f32_16x16x32_bf16 v[98:101], v[130:133], v[186:189], v[98:101]
	v_mfma_f32_16x16x32_bf16 v[94:97], v[138:141], v[186:189], v[94:97]
	v_mfma_f32_16x16x32_bf16 v[82:85], v[130:133], v[194:197], v[82:85]
	v_mfma_f32_16x16x32_bf16 v[78:81], v[138:141], v[194:197], v[78:81]
	s_setprio 0
	s_setprio 1
	v_mfma_f32_16x16x32_bf16 v[126:129], v[146:149], v[166:169], v[126:129]
	v_mfma_f32_16x16x32_bf16 v[122:125], v[158:161], v[166:169], v[122:125]
	v_mfma_f32_16x16x32_bf16 v[106:109], v[146:149], v[174:177], v[106:109]
	v_mfma_f32_16x16x32_bf16 v[102:105], v[158:161], v[174:177], v[102:105]
	v_mfma_f32_16x16x32_bf16 v[90:93], v[146:149], v[182:185], v[90:93]
	v_mfma_f32_16x16x32_bf16 v[86:89], v[158:161], v[182:185], v[86:89]
	v_mfma_f32_16x16x32_bf16 v[74:77], v[146:149], v[190:193], v[74:77]
	v_mfma_f32_16x16x32_bf16 v[70:73], v[158:161], v[190:193], v[70:73]
	v_mfma_f32_16x16x32_bf16 v[126:129], v[154:157], v[170:173], v[126:129]
	v_mfma_f32_16x16x32_bf16 v[122:125], v[162:165], v[170:173], v[122:125]
	v_mfma_f32_16x16x32_bf16 v[106:109], v[154:157], v[178:181], v[106:109]
	v_mfma_f32_16x16x32_bf16 v[102:105], v[162:165], v[178:181], v[102:105]
	v_mfma_f32_16x16x32_bf16 v[90:93], v[154:157], v[186:189], v[90:93]
	v_mfma_f32_16x16x32_bf16 v[86:89], v[162:165], v[186:189], v[86:89]
	v_mfma_f32_16x16x32_bf16 v[74:77], v[154:157], v[194:197], v[74:77]
	v_mfma_f32_16x16x32_bf16 v[70:73], v[162:165], v[194:197], v[70:73]
	s_setprio 0
	s_barrier
	s_add_i32 s20, s33, s36
	v_lshl_add_u64 v[202:203], s[24:25], 0, v[0:1]
	s_mov_b32 m0, s20
	ds_read_b128 v[166:169], v201 offset:16384
	ds_read_b128 v[170:173], v201 offset:17408
	ds_read_b128 v[174:177], v201 offset:18432
	ds_read_b128 v[178:181], v201 offset:19456
	ds_read_b128 v[182:185], v201 offset:20480
	ds_read_b128 v[186:189], v201 offset:21504
	ds_read_b128 v[190:193], v201 offset:22528
	ds_read_b128 v[194:197], v201 offset:23552
	global_load_lds_dwordx4 v0, s[24:25]
	s_add_i32 m0, s20, 0x2000
	s_add_u32 s20, s24, 0x160000
	v_lshl_add_u64 v[214:215], s[24:25], 0, v[208:209]
	s_addc_u32 s21, s25, 0
	s_add_i32 s33, s53, s36
	global_load_lds_dwordx4 v208, s[24:25]
	v_lshl_add_u64 v[216:217], s[20:21], 0, v[0:1]
	s_mov_b32 m0, s33
	v_lshl_add_u64 v[218:219], s[26:27], 0, v[206:207]
	global_load_lds_dwordx4 v0, s[20:21]
	v_lshl_add_u64 v[216:217], s[20:21], 0, v[208:209]
	s_add_i32 m0, s33, 0x2000
	s_nop 0
	global_load_lds_dwordx4 v208, s[20:21]
	v_lshl_add_u64 v[216:217], s[26:27], 0, v[14:15]
	s_mov_b32 m0, s37
	s_nop 0
	global_load_lds_dwordx4 v14, s[26:27]
	s_mov_b32 m0, s38
	s_nop 0
	global_load_lds_dwordx4 v206, s[26:27]
	s_waitcnt vmcnt(8)
	s_waitcnt lgkmcnt(0)
	s_barrier
; #define PG8_STAGE(bufoff, gbase, voff) do { _Pragma("unroll") for (int _i = 0; _i < 2; ++_i) \
;         __builtin_amdgcn_global_load_lds((const unsigned*)((const char*)(gbase) + (voff)[_i]), (PG8_LAS unsigned*)(lds + (bufoff) + ldsw + _i * 8192), 16, 0, 0); } while (0)
; #define PG8_LDA(dst, b, h) do { _Pragma("unroll") for (int m = 0; m < 4; ++m) _Pragma("unroll") for (int k = 0; k < 2; ++k) dst[m][k] = *(const PG8_LAS bf16x8*)(lds + PG8_SA(b, h) + aoff + m * 2048 + k * 1024); } while (0)
; #define PG8_LDB(dst, b, h) do { _Pragma("unroll") for (int n = 0; n < 2; ++n) _Pragma("unroll") for (int k = 0; k < 2; ++k) dst[n][k] = *(const PG8_LAS bf16x8*)(lds + PG8_SB(b, h) + boff + n * 2048 + k * 1024); } while (0)
; #define PG8_MMA(ai, bj, At, Bt) do { __builtin_amdgcn_s_setprio(1); _Pragma("unroll") for (int m = 0; m < 4; ++m) _Pragma("unroll") for (int n = 0; n < 2; ++n) _Pragma("unroll") for (int k = 0; k < 2; ++k) \
;         acc[ai][bj][m][n] = __builtin_amdgcn_mfma_f32_16x16x32_bf16(Bt[n][k], At[m][k], acc[ai][bj][m][n], 0, 0, 0); __builtin_amdgcn_s_setprio(0); } while (0)
; #define PG8_WAIT_V(n) asm volatile("s_waitcnt vmcnt(" #n ")" ::: "memory")
; #define PG8_WAIT_L(n) asm volatile("s_waitcnt lgkmcnt(" #n ")" ::: "memory")
; #define PG8_BAR __builtin_amdgcn_s_barrier()
; #define PG8_SCHED __builtin_amdgcn_sched_barrier(0)
; template <class Epi, class Sched, bool ALIGN_EPI = false, bool SP2 = false>
; __device__ __forceinline__ void gemm_phase(PG8_LAS unsigned char* lds, const Gemm g, const Sched& S, const Epi& E) {
;     ...
;             PG8_WAIT_V(8); PG8_WAIT_L(0); PG8_BAR; PG8_MMA(1, 0, At, B0); PG8_MMA(1, 1, At, B1); PG8_BAR; PG8_SCHED;
;             PG8_LDB(B0, 1, 0); PG8_LDB(B1, 1, 1); PG8_SCHED; PG8_LDA(At, 1, 0); PG8_STAGE(PG8_SA(0, 1), a2 + hstep, voffA);
;             PG8_WAIT_V(8); PG8_WAIT_L(0); PG8_BAR; PG8_MMA(0, 0, At, B0); PG8_MMA(0, 1, At, B1); PG8_BAR; PG8_SCHED;
	s_setprio 1
	s_waitcnt lgkmcnt(0)
	v_mfma_f32_16x16x32_bf16 v[66:69], v[118:121], v[166:169], v[66:69]
	v_mfma_f32_16x16x32_bf16 v[62:65], v[134:137], v[166:169], v[62:65]
	v_mfma_f32_16x16x32_bf16 v[50:53], v[118:121], v[174:177], v[50:53]
	v_mfma_f32_16x16x32_bf16 v[46:49], v[134:137], v[174:177], v[46:49]
	v_mfma_f32_16x16x32_bf16 v[34:37], v[118:121], v[182:185], v[34:37]
	v_mfma_f32_16x16x32_bf16 v[30:33], v[134:137], v[182:185], v[30:33]
	v_mfma_f32_16x16x32_bf16 v[18:21], v[118:121], v[190:193], v[18:21]
	v_mfma_f32_16x16x32_bf16 v[10:13], v[134:137], v[190:193], v[10:13]
	v_mfma_f32_16x16x32_bf16 v[66:69], v[130:133], v[170:173], v[66:69]
	v_mfma_f32_16x16x32_bf16 v[62:65], v[138:141], v[170:173], v[62:65]
	v_mfma_f32_16x16x32_bf16 v[50:53], v[130:133], v[178:181], v[50:53]
	v_mfma_f32_16x16x32_bf16 v[46:49], v[138:141], v[178:181], v[46:49]
	v_mfma_f32_16x16x32_bf16 v[34:37], v[130:133], v[186:189], v[34:37]
	v_mfma_f32_16x16x32_bf16 v[30:33], v[138:141], v[186:189], v[30:33]
	v_mfma_f32_16x16x32_bf16 v[18:21], v[130:133], v[194:197], v[18:21]
	v_mfma_f32_16x16x32_bf16 v[10:13], v[138:141], v[194:197], v[10:13]
	s_setprio 0
	s_setprio 1
	v_mfma_f32_16x16x32_bf16 v[58:61], v[146:149], v[166:169], v[58:61]
	v_mfma_f32_16x16x32_bf16 v[54:57], v[158:161], v[166:169], v[54:57]
	v_mfma_f32_16x16x32_bf16 v[42:45], v[146:149], v[174:177], v[42:45]
	v_mfma_f32_16x16x32_bf16 v[38:41], v[158:161], v[174:177], v[38:41]
	v_mfma_f32_16x16x32_bf16 v[26:29], v[146:149], v[182:185], v[26:29]
	v_mfma_f32_16x16x32_bf16 v[22:25], v[158:161], v[182:185], v[22:25]
	v_mfma_f32_16x16x32_bf16 v[6:9], v[146:149], v[190:193], v[6:9]
	v_mfma_f32_16x16x32_bf16 v[2:5], v[158:161], v[190:193], v[2:5]
	v_mfma_f32_16x16x32_bf16 v[58:61], v[154:157], v[170:173], v[58:61]
	v_mfma_f32_16x16x32_bf16 v[54:57], v[162:165], v[170:173], v[54:57]
	v_mfma_f32_16x16x32_bf16 v[42:45], v[154:157], v[178:181], v[42:45]
	v_mfma_f32_16x16x32_bf16 v[38:41], v[162:165], v[178:181], v[38:41]
	v_mfma_f32_16x16x32_bf16 v[26:29], v[154:157], v[186:189], v[26:29]
	v_mfma_f32_16x16x32_bf16 v[22:25], v[162:165], v[186:189], v[22:25]
	v_mfma_f32_16x16x32_bf16 v[6:9], v[154:157], v[194:197], v[6:9]
	v_mfma_f32_16x16x32_bf16 v[2:5], v[162:165], v[194:197], v[2:5]
	s_setprio 0
	s_barrier
	s_add_i32 s33, 0, 0x18000
	s_add_i32 s53, 0, 0x1c000
	v_add_u32_e32 v138, s33, v199
	v_add_u32_e32 v162, s53, v199
	ds_read_b128 v[118:121], v138
	ds_read_b128 v[130:133], v138 offset:1024
	ds_read_b128 v[134:137], v138 offset:2048
	ds_read_b128 v[138:141], v138 offset:3072
	ds_read_b128 v[146:149], v162
	ds_read_b128 v[154:157], v162 offset:1024
	ds_read_b128 v[158:161], v162 offset:2048
	ds_read_b128 v[162:165], v162 offset:3072
	s_add_u32 s20, s26, 0x160000
	s_addc_u32 s21, s27, 0
	s_mov_b32 m0, s39
	v_lshl_add_u64 v[220:221], s[20:21], 0, v[14:15]
	ds_read_b128 v[166:169], v201 offset:32768
	ds_read_b128 v[170:173], v201 offset:33792
	ds_read_b128 v[174:177], v201 offset:34816
	ds_read_b128 v[178:181], v201 offset:35840
	ds_read_b128 v[182:185], v201 offset:36864
	ds_read_b128 v[186:189], v201 offset:37888
	ds_read_b128 v[190:193], v201 offset:38912
	ds_read_b128 v[194:197], v201 offset:39936
	global_load_lds_dwordx4 v14, s[20:21]
	v_lshl_add_u64 v[220:221], s[20:21], 0, v[206:207]
	s_mov_b32 m0, s40
	s_nop 0
	global_load_lds_dwordx4 v206, s[20:21]
	s_waitcnt vmcnt(8)
	s_waitcnt lgkmcnt(0)
	s_barrier
	s_setprio 1
	s_waitcnt lgkmcnt(0)
	v_mfma_f32_16x16x32_bf16 v[150:153], v[118:121], v[166:169], v[150:153]
	v_mfma_f32_16x16x32_bf16 v[142:145], v[134:137], v[166:169], v[142:145]
	v_mfma_f32_16x16x32_bf16 v[114:117], v[118:121], v[174:177], v[114:117]
	v_mfma_f32_16x16x32_bf16 v[110:113], v[134:137], v[174:177], v[110:113]
	v_mfma_f32_16x16x32_bf16 v[98:101], v[118:121], v[182:185], v[98:101]
	v_mfma_f32_16x16x32_bf16 v[94:97], v[134:137], v[182:185], v[94:97]
	v_mfma_f32_16x16x32_bf16 v[82:85], v[118:121], v[190:193], v[82:85]
	v_mfma_f32_16x16x32_bf16 v[78:81], v[134:137], v[190:193], v[78:81]
	v_mfma_f32_16x16x32_bf16 v[150:153], v[130:133], v[170:173], v[150:153]
	v_mfma_f32_16x16x32_bf16 v[142:145], v[138:141], v[170:173], v[142:145]
	v_mfma_f32_16x16x32_bf16 v[114:117], v[130:133], v[178:181], v[114:117]
	v_mfma_f32_16x16x32_bf16 v[110:113], v[138:141], v[178:181], v[110:113]
	v_mfma_f32_16x16x32_bf16 v[98:101], v[130:133], v[186:189], v[98:101]
	v_mfma_f32_16x16x32_bf16 v[94:97], v[138:141], v[186:189], v[94:97]
	v_mfma_f32_16x16x32_bf16 v[82:85], v[130:133], v[194:197], v[82:85]
	v_mfma_f32_16x16x32_bf16 v[78:81], v[138:141], v[194:197], v[78:81]
	s_setprio 0
	s_setprio 1
	v_mfma_f32_16x16x32_bf16 v[126:129], v[146:149], v[166:169], v[126:129]
	v_mfma_f32_16x16x32_bf16 v[122:125], v[158:161], v[166:169], v[122:125]
	v_mfma_f32_16x16x32_bf16 v[106:109], v[146:149], v[174:177], v[106:109]
	v_mfma_f32_16x16x32_bf16 v[102:105], v[158:161], v[174:177], v[102:105]
	v_mfma_f32_16x16x32_bf16 v[90:93], v[146:149], v[182:185], v[90:93]
	v_mfma_f32_16x16x32_bf16 v[86:89], v[158:161], v[182:185], v[86:89]
	v_mfma_f32_16x16x32_bf16 v[74:77], v[146:149], v[190:193], v[74:77]
	v_mfma_f32_16x16x32_bf16 v[70:73], v[158:161], v[190:193], v[70:73]
	v_mfma_f32_16x16x32_bf16 v[126:129], v[154:157], v[170:173], v[126:129]
	v_mfma_f32_16x16x32_bf16 v[122:125], v[162:165], v[170:173], v[122:125]
	v_mfma_f32_16x16x32_bf16 v[106:109], v[154:157], v[178:181], v[106:109]
	v_mfma_f32_16x16x32_bf16 v[102:105], v[162:165], v[178:181], v[102:105]
	v_mfma_f32_16x16x32_bf16 v[90:93], v[154:157], v[186:189], v[90:93]
	v_mfma_f32_16x16x32_bf16 v[86:89], v[162:165], v[186:189], v[86:89]
	v_mfma_f32_16x16x32_bf16 v[74:77], v[154:157], v[194:197], v[74:77]
	v_mfma_f32_16x16x32_bf16 v[70:73], v[162:165], v[194:197], v[70:73]
	s_setprio 0
	s_barrier
; #define PG8_STAGE(bufoff, gbase, voff) do { _Pragma("unroll") for (int _i = 0; _i < 2; ++_i) \
;         __builtin_amdgcn_global_load_lds((const unsigned*)((const char*)(gbase) + (voff)[_i]), (PG8_LAS unsigned*)(lds + (bufoff) + ldsw + _i * 8192), 16, 0, 0); } while (0)
; #define PG8_LDA(dst, b, h) do { _Pragma("unroll") for (int m = 0; m < 4; ++m) _Pragma("unroll") for (int k = 0; k < 2; ++k) dst[m][k] = *(const PG8_LAS bf16x8*)(lds + PG8_SA(b, h) + aoff + m * 2048 + k * 1024); } while (0)
; #define PG8_MMA(ai, bj, At, Bt) do { __builtin_amdgcn_s_setprio(1); _Pragma("unroll") for (int m = 0; m < 4; ++m) _Pragma("unroll") for (int n = 0; n < 2; ++n) _Pragma("unroll") for (int k = 0; k < 2; ++k) \
;         acc[ai][bj][m][n] = __builtin_amdgcn_mfma_f32_16x16x32_bf16(Bt[n][k], At[m][k], acc[ai][bj][m][n], 0, 0, 0); __builtin_amdgcn_s_setprio(0); } while (0)
; #define PG8_WAIT_V(n) asm volatile("s_waitcnt vmcnt(" #n ")" ::: "memory")
; #define PG8_WAIT_L(n) asm volatile("s_waitcnt lgkmcnt(" #n ")" ::: "memory")
; #define PG8_BAR __builtin_amdgcn_s_barrier()
; #define PG8_SCHED __builtin_amdgcn_sched_barrier(0)
; template <class Epi, class Sched, bool ALIGN_EPI = false, bool SP2 = false>
; __device__ __forceinline__ void gemm_phase(PG8_LAS unsigned char* lds, const Gemm g, const Sched& S, const Epi& E) {
;     ...
;             PG8_LDA(At, 1, 1); PG8_STAGE(PG8_SB(1, 0), b3, voffB); PG8_STAGE(PG8_SB(1, 1), b3 + hstep, voffB); PG8_STAGE(PG8_SA(1, 0), a3, voffA);
;             PG8_WAIT_V(8); PG8_WAIT_L(0); PG8_BAR; PG8_MMA(1, 0, At, B0); PG8_MMA(1, 1, At, B1); PG8_BAR; PG8_SCHED;
;     ...
;         if constexpr (ALIGN_EPI) { if (wr == 0) PG8_BAR; }
	s_add_i32 s20, s33, s36
	v_lshl_add_u64 v[202:203], v[202:203], 0, s[92:93]
	s_mov_b32 m0, s20
	ds_read_b128 v[166:169], v201 offset:49152
	ds_read_b128 v[170:173], v201 offset:50176
	ds_read_b128 v[174:177], v201 offset:51200
	ds_read_b128 v[178:181], v201 offset:52224
	ds_read_b128 v[182:185], v201 offset:53248
	ds_read_b128 v[186:189], v201 offset:54272
	ds_read_b128 v[190:193], v201 offset:55296
	ds_read_b128 v[194:197], v201 offset:56320
	global_load_lds_dwordx4 v[202:203], off
	s_add_i32 m0, s20, 0x2000
	s_add_u32 s20, s24, 0x160080
	v_lshl_add_u64 v[202:203], v[214:215], 0, s[92:93]
	s_addc_u32 s21, s25, 0
	s_add_i32 s24, s53, s36
	global_load_lds_dwordx4 v[202:203], off
	v_lshl_add_u64 v[202:203], s[20:21], 0, v[0:1]
	s_mov_b32 m0, s24
	s_nop 0
	global_load_lds_dwordx4 v0, s[20:21]
	v_lshl_add_u64 v[202:203], s[20:21], 0, v[208:209]
	s_add_i32 m0, s24, 0x2000
	s_nop 0
	global_load_lds_dwordx4 v208, s[20:21]
	v_lshl_add_u64 v[202:203], v[216:217], 0, s[92:93]
	s_mov_b32 m0, s42
	s_nop 0
	global_load_lds_dwordx4 v[202:203], off
	v_lshl_add_u64 v[202:203], v[218:219], 0, s[92:93]
	s_mov_b32 m0, s43
	s_nop 0
	global_load_lds_dwordx4 v[202:203], off
	s_waitcnt vmcnt(8)
	s_waitcnt lgkmcnt(0)
	s_barrier
	s_setprio 1
	s_waitcnt lgkmcnt(0)
	v_mfma_f32_16x16x32_bf16 v[66:69], v[118:121], v[166:169], v[66:69]
	v_mfma_f32_16x16x32_bf16 v[62:65], v[134:137], v[166:169], v[62:65]
	v_mfma_f32_16x16x32_bf16 v[50:53], v[118:121], v[174:177], v[50:53]
	v_mfma_f32_16x16x32_bf16 v[46:49], v[134:137], v[174:177], v[46:49]
	v_mfma_f32_16x16x32_bf16 v[34:37], v[118:121], v[182:185], v[34:37]
	v_mfma_f32_16x16x32_bf16 v[30:33], v[134:137], v[182:185], v[30:33]
	v_mfma_f32_16x16x32_bf16 v[18:21], v[118:121], v[190:193], v[18:21]
	v_mfma_f32_16x16x32_bf16 v[10:13], v[134:137], v[190:193], v[10:13]
	v_mfma_f32_16x16x32_bf16 v[66:69], v[130:133], v[170:173], v[66:69]
	v_mfma_f32_16x16x32_bf16 v[62:65], v[138:141], v[170:173], v[62:65]
	v_mfma_f32_16x16x32_bf16 v[50:53], v[130:133], v[178:181], v[50:53]
	v_mfma_f32_16x16x32_bf16 v[46:49], v[138:141], v[178:181], v[46:49]
	v_mfma_f32_16x16x32_bf16 v[34:37], v[130:133], v[186:189], v[34:37]
	v_mfma_f32_16x16x32_bf16 v[30:33], v[138:141], v[186:189], v[30:33]
	v_mfma_f32_16x16x32_bf16 v[18:21], v[130:133], v[194:197], v[18:21]
	v_mfma_f32_16x16x32_bf16 v[10:13], v[138:141], v[194:197], v[10:13]
	s_setprio 0
	s_setprio 1
	v_mfma_f32_16x16x32_bf16 v[58:61], v[146:149], v[166:169], v[58:61]
	v_mfma_f32_16x16x32_bf16 v[54:57], v[158:161], v[166:169], v[54:57]
	v_mfma_f32_16x16x32_bf16 v[42:45], v[146:149], v[174:177], v[42:45]
	v_mfma_f32_16x16x32_bf16 v[38:41], v[158:161], v[174:177], v[38:41]
	v_mfma_f32_16x16x32_bf16 v[26:29], v[146:149], v[182:185], v[26:29]
	v_mfma_f32_16x16x32_bf16 v[22:25], v[158:161], v[182:185], v[22:25]
	v_mfma_f32_16x16x32_bf16 v[6:9], v[146:149], v[190:193], v[6:9]
	v_mfma_f32_16x16x32_bf16 v[2:5], v[158:161], v[190:193], v[2:5]
	v_mfma_f32_16x16x32_bf16 v[58:61], v[154:157], v[170:173], v[58:61]
	v_mfma_f32_16x16x32_bf16 v[54:57], v[162:165], v[170:173], v[54:57]
	v_mfma_f32_16x16x32_bf16 v[42:45], v[154:157], v[178:181], v[42:45]
	v_mfma_f32_16x16x32_bf16 v[38:41], v[162:165], v[178:181], v[38:41]
	v_mfma_f32_16x16x32_bf16 v[26:29], v[154:157], v[186:189], v[26:29]
	v_mfma_f32_16x16x32_bf16 v[22:25], v[162:165], v[186:189], v[22:25]
	v_mfma_f32_16x16x32_bf16 v[6:9], v[154:157], v[194:197], v[6:9]
	v_mfma_f32_16x16x32_bf16 v[2:5], v[162:165], v[194:197], v[2:5]
	s_setprio 0
	s_barrier
	s_add_i32 s52, s52, 2
	s_add_u32 s50, s50, 0x100
	s_addc_u32 s51, s51, 0
	s_cmpk_gt_u32 s52, 0x55
	s_mov_b64 s[20:21], s[22:23]
	s_cbranch_scc0 .LBB0_482
	s_and_b64 vcc, exec, s[14:15]
	s_cbranch_vccz .LBB0_485
	s_barrier

; #define PG8_STAGE(bufoff, gbase, voff) do { _Pragma("unroll") for (int _i = 0; _i < 2; ++_i) \
;         __builtin_amdgcn_global_load_lds((const unsigned*)((const char*)(gbase) + (voff)[_i]), (PG8_LAS unsigned*)(lds + (bufoff) + ldsw + _i * 8192), 16, 0, 0); } while (0)
; #define PG8_LDA(dst, b, h) do { _Pragma("unroll") for (int m = 0; m < 4; ++m) _Pragma("unroll") for (int k = 0; k < 2; ++k) dst[m][k] = *(const PG8_LAS bf16x8*)(lds + PG8_SA(b, h) + aoff + m * 2048 + k * 1024); } while (0)
; #define PG8_LDB(dst, b, h) do { _Pragma("unroll") for (int n = 0; n < 2; ++n) _Pragma("unroll") for (int k = 0; k < 2; ++k) dst[n][k] = *(const PG8_LAS bf16x8*)(lds + PG8_SB(b, h) + boff + n * 2048 + k * 1024); } while (0)
; #define PG8_MMA(ai, bj, At, Bt) do { __builtin_amdgcn_s_setprio(1); _Pragma("unroll") for (int m = 0; m < 4; ++m) _Pragma("unroll") for (int n = 0; n < 2; ++n) _Pragma("unroll") for (int k = 0; k < 2; ++k) \
;         acc[ai][bj][m][n] = __builtin_amdgcn_mfma_f32_16x16x32_bf16(Bt[n][k], At[m][k], acc[ai][bj][m][n], 0, 0, 0); __builtin_amdgcn_s_setprio(0); } while (0)
; #define PG8_WAIT_V(n) asm volatile("s_waitcnt vmcnt(" #n ")" ::: "memory")
; #define PG8_WAIT_L(n) asm volatile("s_waitcnt lgkmcnt(" #n ")" ::: "memory")
; template <class Epi, class Sched, bool ALIGN_EPI = false, bool SP2 = false>
; __device__ __forceinline__ void gemm_phase(PG8_LAS unsigned char* lds, const Gemm g, const Sched& S, const Epi& E) {
;     ...
;         for (int t = 0; t < nt; t += 2) {
;             const bool last = (t == nt - 2);
;             const char* a1 = cA + (size_t)(t + 1) * kstep;
;             const char* a2 = last ? nA : cA + (size_t)(t + 2) * kstep; const char* b2 = last ? nB : cB + (size_t)(t + 2) * kstep;
;             const char* a3 = a2 + kstep; const char* b3 = b2 + kstep;
;             if (last && has_next) S.a_ready(nxt);
;             if constexpr (Epi::MID) { if (t == nt / 2) E.mid(acc, cur, wr, wc, fr, fq); }
;             if constexpr (SP2) {
;             PG8_LDB(B0, 0, 0); PG8_LDB(B1, 0, 1); PG8_SCHED; PG8_LDA(At, 0, 0); PG8_STAGE(PG8_SA(1, 1), a1 + hstep, voffA);
;             PG8_WAIT_V(8); PG8_WAIT_L(0); PG8_BAR; PG8_MMA(0, 0, At, B0); PG8_MMA(0, 1, At, B1); PG8_BAR; PG8_SCHED;
;             PG8_LDA(At, 0, 1); PG8_STAGE(PG8_SB(0, 0), b2, voffB); PG8_STAGE(PG8_SB(0, 1), b2 + hstep, voffB); PG8_STAGE(PG8_SA(0, 0), a2, voffA);
.LBB0_588:
	s_add_u32 s33, s40, 0xfff80080
	s_addc_u32 s44, s41, -1
	s_add_i32 s50, 0, 0x10000
	s_cmp_eq_u32 s49, 28
	s_cselect_b32 s47, s5, s44
	s_cselect_b32 s46, s13, s33
	v_add_u32_e32 v0, s50, v153
	s_cselect_b32 s45, s31, s48
	s_cselect_b32 s44, s35, s43
	s_add_i32 s33, 0, 0x14000
	ds_read_b128 v[134:137], v0
	ds_read_b128 v[138:141], v0 offset:1024
	ds_read_b128 v[142:145], v0 offset:2048
	s_waitcnt lgkmcnt(0)
	ds_read_b128 v[168:171], v0 offset:3072
	v_add_u32_e32 v0, s33, v153
	ds_read_b128 v[172:175], v0
	ds_read_b128 v[176:179], v0 offset:1024
	ds_read_b128 v[180:183], v0 offset:2048
	ds_read_b128 v[184:187], v0 offset:3072
	v_lshl_add_u64 v[192:193], s[40:41], 0, v[166:167]
	s_add_i32 m0, s62, 0xc000
	ds_read_b128 v[188:191], v194
	ds_read_b128 v[196:199], v194 offset:1024
	ds_read_b128 v[200:203], v194 offset:2048
	ds_read_b128 v[206:209], v194 offset:3072
	ds_read_b128 v[210:213], v194 offset:4096
	ds_read_b128 v[214:217], v194 offset:5120
	ds_read_b128 v[218:221], v194 offset:6144
	ds_read_b128 v[222:225], v194 offset:7168
	global_load_lds_dwordx4 v166, s[40:41]
	v_lshl_add_u64 v[192:193], s[40:41], 0, v[164:165]
	s_add_i32 m0, s62, 0xe000
	s_nop 0
	global_load_lds_dwordx4 v164, s[40:41]
	s_waitcnt vmcnt(8)
	s_waitcnt lgkmcnt(0)
	s_barrier
	s_setprio 1
	s_waitcnt lgkmcnt(0)
	v_mfma_f32_16x16x32_bf16 v[74:77], v[134:137], v[188:191], v[74:77]
	v_mfma_f32_16x16x32_bf16 v[62:65], v[142:145], v[188:191], v[62:65]
	v_mfma_f32_16x16x32_bf16 v[58:61], v[134:137], v[200:203], v[58:61]
	v_mfma_f32_16x16x32_bf16 v[54:57], v[142:145], v[200:203], v[54:57]
	v_mfma_f32_16x16x32_bf16 v[50:53], v[134:137], v[210:213], v[50:53]
	v_mfma_f32_16x16x32_bf16 v[46:49], v[142:145], v[210:213], v[46:49]
	v_mfma_f32_16x16x32_bf16 v[42:45], v[134:137], v[218:221], v[42:45]
	v_mfma_f32_16x16x32_bf16 v[38:41], v[142:145], v[218:221], v[38:41]
	v_mfma_f32_16x16x32_bf16 v[74:77], v[138:141], v[196:199], v[74:77]
	v_mfma_f32_16x16x32_bf16 v[62:65], v[168:171], v[196:199], v[62:65]
	v_mfma_f32_16x16x32_bf16 v[58:61], v[138:141], v[206:209], v[58:61]
	v_mfma_f32_16x16x32_bf16 v[54:57], v[168:171], v[206:209], v[54:57]
	v_mfma_f32_16x16x32_bf16 v[50:53], v[138:141], v[214:217], v[50:53]
	v_mfma_f32_16x16x32_bf16 v[46:49], v[168:171], v[214:217], v[46:49]
	v_mfma_f32_16x16x32_bf16 v[42:45], v[138:141], v[222:225], v[42:45]
	v_mfma_f32_16x16x32_bf16 v[38:41], v[168:171], v[222:225], v[38:41]
	s_setprio 0
	s_setprio 1
	v_mfma_f32_16x16x32_bf16 v[130:133], v[172:175], v[188:191], v[130:133]
	v_mfma_f32_16x16x32_bf16 v[126:129], v[180:183], v[188:191], v[126:129]
	v_mfma_f32_16x16x32_bf16 v[122:125], v[172:175], v[200:203], v[122:125]
	v_mfma_f32_16x16x32_bf16 v[118:121], v[180:183], v[200:203], v[118:121]
	v_mfma_f32_16x16x32_bf16 v[114:117], v[172:175], v[210:213], v[114:117]
	v_mfma_f32_16x16x32_bf16 v[110:113], v[180:183], v[210:213], v[110:113]
	v_mfma_f32_16x16x32_bf16 v[106:109], v[172:175], v[218:221], v[106:109]
	v_mfma_f32_16x16x32_bf16 v[102:105], v[180:183], v[218:221], v[102:105]
	v_mfma_f32_16x16x32_bf16 v[130:133], v[176:179], v[196:199], v[130:133]
	v_mfma_f32_16x16x32_bf16 v[126:129], v[184:187], v[196:199], v[126:129]
	v_mfma_f32_16x16x32_bf16 v[122:125], v[176:179], v[206:209], v[122:125]
	v_mfma_f32_16x16x32_bf16 v[118:121], v[184:187], v[206:209], v[118:121]
	v_mfma_f32_16x16x32_bf16 v[114:117], v[176:179], v[214:217], v[114:117]
	v_mfma_f32_16x16x32_bf16 v[110:113], v[184:187], v[214:217], v[110:113]
	v_mfma_f32_16x16x32_bf16 v[106:109], v[176:179], v[222:225], v[106:109]
	v_mfma_f32_16x16x32_bf16 v[102:105], v[184:187], v[222:225], v[102:105]
	s_setprio 0
	s_barrier
	s_add_i32 s50, s50, s61
	v_lshl_add_u64 v[192:193], s[44:45], 0, v[146:147]
	s_mov_b32 m0, s50
	ds_read_b128 v[188:191], v194 offset:16384
	ds_read_b128 v[196:199], v194 offset:17408
	ds_read_b128 v[200:203], v194 offset:18432
	ds_read_b128 v[206:209], v194 offset:19456
	ds_read_b128 v[210:213], v194 offset:20480
	ds_read_b128 v[214:217], v194 offset:21504
	ds_read_b128 v[218:221], v194 offset:22528
	ds_read_b128 v[222:225], v194 offset:23552
	global_load_lds_dwordx4 v146, s[44:45]
	s_add_i32 m0, s50, 0x2000
	s_add_u32 s50, s44, 0x80000
	v_lshl_add_u64 v[226:227], s[44:45], 0, v[150:151]
	s_addc_u32 s51, s45, 0
	s_add_i32 s33, s33, s61
	global_load_lds_dwordx4 v150, s[44:45]
	v_lshl_add_u64 v[228:229], s[50:51], 0, v[146:147]
	s_mov_b32 m0, s33
	v_lshl_add_u64 v[230:231], s[46:47], 0, v[148:149]
	global_load_lds_dwordx4 v146, s[50:51]
	v_lshl_add_u64 v[228:229], s[50:51], 0, v[150:151]
	s_add_i32 m0, s33, 0x2000
	s_nop 0
	global_load_lds_dwordx4 v150, s[50:51]
	v_lshl_add_u64 v[228:229], s[46:47], 0, v[14:15]
	s_mov_b32 m0, s62
	s_nop 0
	global_load_lds_dwordx4 v14, s[46:47]
	s_mov_b32 m0, s63
	s_nop 0
	global_load_lds_dwordx4 v148, s[46:47]
	s_waitcnt vmcnt(8)
	s_waitcnt lgkmcnt(0)
	s_barrier
; #define PG8_STAGE(bufoff, gbase, voff) do { _Pragma("unroll") for (int _i = 0; _i < 2; ++_i) \
;         __builtin_amdgcn_global_load_lds((const unsigned*)((const char*)(gbase) + (voff)[_i]), (PG8_LAS unsigned*)(lds + (bufoff) + ldsw + _i * 8192), 16, 0, 0); } while (0)
; #define PG8_LDA(dst, b, h) do { _Pragma("unroll") for (int m = 0; m < 4; ++m) _Pragma("unroll") for (int k = 0; k < 2; ++k) dst[m][k] = *(const PG8_LAS bf16x8*)(lds + PG8_SA(b, h) + aoff + m * 2048 + k * 1024); } while (0)
; #define PG8_LDB(dst, b, h) do { _Pragma("unroll") for (int n = 0; n < 2; ++n) _Pragma("unroll") for (int k = 0; k < 2; ++k) dst[n][k] = *(const PG8_LAS bf16x8*)(lds + PG8_SB(b, h) + boff + n * 2048 + k * 1024); } while (0)
; #define PG8_MMA(ai, bj, At, Bt) do { __builtin_amdgcn_s_setprio(1); _Pragma("unroll") for (int m = 0; m < 4; ++m) _Pragma("unroll") for (int n = 0; n < 2; ++n) _Pragma("unroll") for (int k = 0; k < 2; ++k) \
;         acc[ai][bj][m][n] = __builtin_amdgcn_mfma_f32_16x16x32_bf16(Bt[n][k], At[m][k], acc[ai][bj][m][n], 0, 0, 0); __builtin_amdgcn_s_setprio(0); } while (0)
; #define PG8_WAIT_V(n) asm volatile("s_waitcnt vmcnt(" #n ")" ::: "memory")
; #define PG8_WAIT_L(n) asm volatile("s_waitcnt lgkmcnt(" #n ")" ::: "memory")
; #define PG8_BAR __builtin_amdgcn_s_barrier()
; #define PG8_SCHED __builtin_amdgcn_sched_barrier(0)
; template <class Epi, class Sched, bool ALIGN_EPI = false, bool SP2 = false>
; __device__ __forceinline__ void gemm_phase(PG8_LAS unsigned char* lds, const Gemm g, const Sched& S, const Epi& E) {
;     ...
;             PG8_WAIT_V(8); PG8_WAIT_L(0); PG8_BAR; PG8_MMA(1, 0, At, B0); PG8_MMA(1, 1, At, B1); PG8_BAR; PG8_SCHED;
;             PG8_LDB(B0, 1, 0); PG8_LDB(B1, 1, 1); PG8_SCHED; PG8_LDA(At, 1, 0); PG8_STAGE(PG8_SA(0, 1), a2 + hstep, voffA);
;             PG8_WAIT_V(8); PG8_WAIT_L(0); PG8_BAR; PG8_MMA(0, 0, At, B0); PG8_MMA(0, 1, At, B1); PG8_BAR; PG8_SCHED;
	s_setprio 1
	s_waitcnt lgkmcnt(0)
	v_mfma_f32_16x16x32_bf16 v[34:37], v[134:137], v[188:191], v[34:37]
	v_mfma_f32_16x16x32_bf16 v[30:33], v[142:145], v[188:191], v[30:33]
	v_mfma_f32_16x16x32_bf16 v[26:29], v[134:137], v[200:203], v[26:29]
	v_mfma_f32_16x16x32_bf16 v[22:25], v[142:145], v[200:203], v[22:25]
	v_mfma_f32_16x16x32_bf16 v[18:21], v[134:137], v[210:213], v[18:21]
	v_mfma_f32_16x16x32_bf16 v[10:13], v[142:145], v[210:213], v[10:13]
	v_mfma_f32_16x16x32_bf16 v[6:9], v[134:137], v[218:221], v[6:9]
	v_mfma_f32_16x16x32_bf16 v[2:5], v[142:145], v[218:221], v[2:5]
	v_mfma_f32_16x16x32_bf16 v[34:37], v[138:141], v[196:199], v[34:37]
	v_mfma_f32_16x16x32_bf16 v[30:33], v[168:171], v[196:199], v[30:33]
	v_mfma_f32_16x16x32_bf16 v[26:29], v[138:141], v[206:209], v[26:29]
	v_mfma_f32_16x16x32_bf16 v[22:25], v[168:171], v[206:209], v[22:25]
	v_mfma_f32_16x16x32_bf16 v[18:21], v[138:141], v[214:217], v[18:21]
	v_mfma_f32_16x16x32_bf16 v[10:13], v[168:171], v[214:217], v[10:13]
	v_mfma_f32_16x16x32_bf16 v[6:9], v[138:141], v[222:225], v[6:9]
	v_mfma_f32_16x16x32_bf16 v[2:5], v[168:171], v[222:225], v[2:5]
	s_setprio 0
	s_setprio 1
	v_mfma_f32_16x16x32_bf16 v[98:101], v[172:175], v[188:191], v[98:101]
	v_mfma_f32_16x16x32_bf16 v[94:97], v[180:183], v[188:191], v[94:97]
	v_mfma_f32_16x16x32_bf16 v[90:93], v[172:175], v[200:203], v[90:93]
	v_mfma_f32_16x16x32_bf16 v[86:89], v[180:183], v[200:203], v[86:89]
	v_mfma_f32_16x16x32_bf16 v[82:85], v[172:175], v[210:213], v[82:85]
	v_mfma_f32_16x16x32_bf16 v[78:81], v[180:183], v[210:213], v[78:81]
	v_mfma_f32_16x16x32_bf16 v[70:73], v[172:175], v[218:221], v[70:73]
	v_mfma_f32_16x16x32_bf16 v[66:69], v[180:183], v[218:221], v[66:69]
	v_mfma_f32_16x16x32_bf16 v[98:101], v[176:179], v[196:199], v[98:101]
	v_mfma_f32_16x16x32_bf16 v[94:97], v[184:187], v[196:199], v[94:97]
	v_mfma_f32_16x16x32_bf16 v[90:93], v[176:179], v[206:209], v[90:93]
	v_mfma_f32_16x16x32_bf16 v[86:89], v[184:187], v[206:209], v[86:89]
	v_mfma_f32_16x16x32_bf16 v[82:85], v[176:179], v[214:217], v[82:85]
	v_mfma_f32_16x16x32_bf16 v[78:81], v[184:187], v[214:217], v[78:81]
	v_mfma_f32_16x16x32_bf16 v[70:73], v[176:179], v[222:225], v[70:73]
	v_mfma_f32_16x16x32_bf16 v[66:69], v[184:187], v[222:225], v[66:69]
	s_setprio 0
	s_barrier
	s_add_i32 s33, 0, 0x18000
	v_add_u32_e32 v0, s33, v153
	s_add_i32 s50, 0, 0x1c000
	ds_read_b128 v[134:137], v0
	ds_read_b128 v[138:141], v0 offset:1024
	ds_read_b128 v[142:145], v0 offset:2048
	ds_read_b128 v[168:171], v0 offset:3072
	v_add_u32_e32 v0, s50, v153
	ds_read_b128 v[172:175], v0
	ds_read_b128 v[176:179], v0 offset:1024
	ds_read_b128 v[180:183], v0 offset:2048
	ds_read_b128 v[184:187], v0 offset:3072
	s_add_u32 s46, s46, 0x80000
	s_addc_u32 s47, s47, 0
	s_mov_b32 m0, s64
	v_lshl_add_u64 v[232:233], s[46:47], 0, v[14:15]
	ds_read_b128 v[188:191], v194 offset:32768
	ds_read_b128 v[196:199], v194 offset:33792
	ds_read_b128 v[200:203], v194 offset:34816
	ds_read_b128 v[206:209], v194 offset:35840
	ds_read_b128 v[210:213], v194 offset:36864
	ds_read_b128 v[214:217], v194 offset:37888
	ds_read_b128 v[218:221], v194 offset:38912
	ds_read_b128 v[222:225], v194 offset:39936
	global_load_lds_dwordx4 v14, s[46:47]
	v_lshl_add_u64 v[232:233], s[46:47], 0, v[148:149]
	s_mov_b32 m0, s65
	s_nop 0
	global_load_lds_dwordx4 v148, s[46:47]
	s_waitcnt vmcnt(8)
	s_waitcnt lgkmcnt(0)
	s_barrier
	s_setprio 1
	s_waitcnt lgkmcnt(0)
	v_mfma_f32_16x16x32_bf16 v[74:77], v[134:137], v[188:191], v[74:77]
	v_mfma_f32_16x16x32_bf16 v[62:65], v[142:145], v[188:191], v[62:65]
	v_mfma_f32_16x16x32_bf16 v[58:61], v[134:137], v[200:203], v[58:61]
	v_mfma_f32_16x16x32_bf16 v[54:57], v[142:145], v[200:203], v[54:57]
	v_mfma_f32_16x16x32_bf16 v[50:53], v[134:137], v[210:213], v[50:53]
	v_mfma_f32_16x16x32_bf16 v[46:49], v[142:145], v[210:213], v[46:49]
	v_mfma_f32_16x16x32_bf16 v[42:45], v[134:137], v[218:221], v[42:45]
	v_mfma_f32_16x16x32_bf16 v[38:41], v[142:145], v[218:221], v[38:41]
	v_mfma_f32_16x16x32_bf16 v[74:77], v[138:141], v[196:199], v[74:77]
	v_mfma_f32_16x16x32_bf16 v[62:65], v[168:171], v[196:199], v[62:65]
	v_mfma_f32_16x16x32_bf16 v[58:61], v[138:141], v[206:209], v[58:61]
	v_mfma_f32_16x16x32_bf16 v[54:57], v[168:171], v[206:209], v[54:57]
	v_mfma_f32_16x16x32_bf16 v[50:53], v[138:141], v[214:217], v[50:53]
	v_mfma_f32_16x16x32_bf16 v[46:49], v[168:171], v[214:217], v[46:49]
	v_mfma_f32_16x16x32_bf16 v[42:45], v[138:141], v[222:225], v[42:45]
	v_mfma_f32_16x16x32_bf16 v[38:41], v[168:171], v[222:225], v[38:41]
	s_setprio 0
	s_setprio 1
	v_mfma_f32_16x16x32_bf16 v[130:133], v[172:175], v[188:191], v[130:133]
	v_mfma_f32_16x16x32_bf16 v[126:129], v[180:183], v[188:191], v[126:129]
	v_mfma_f32_16x16x32_bf16 v[122:125], v[172:175], v[200:203], v[122:125]
	v_mfma_f32_16x16x32_bf16 v[118:121], v[180:183], v[200:203], v[118:121]
	v_mfma_f32_16x16x32_bf16 v[114:117], v[172:175], v[210:213], v[114:117]
	v_mfma_f32_16x16x32_bf16 v[110:113], v[180:183], v[210:213], v[110:113]
	v_mfma_f32_16x16x32_bf16 v[106:109], v[172:175], v[218:221], v[106:109]
	v_mfma_f32_16x16x32_bf16 v[102:105], v[180:183], v[218:221], v[102:105]
	v_mfma_f32_16x16x32_bf16 v[130:133], v[176:179], v[196:199], v[130:133]
	v_mfma_f32_16x16x32_bf16 v[126:129], v[184:187], v[196:199], v[126:129]
	v_mfma_f32_16x16x32_bf16 v[122:125], v[176:179], v[206:209], v[122:125]
	v_mfma_f32_16x16x32_bf16 v[118:121], v[184:187], v[206:209], v[118:121]
	v_mfma_f32_16x16x32_bf16 v[114:117], v[176:179], v[214:217], v[114:117]
	v_mfma_f32_16x16x32_bf16 v[110:113], v[184:187], v[214:217], v[110:113]
	v_mfma_f32_16x16x32_bf16 v[106:109], v[176:179], v[222:225], v[106:109]
	v_mfma_f32_16x16x32_bf16 v[102:105], v[184:187], v[222:225], v[102:105]
	s_setprio 0
	s_barrier
; #define PG8_STAGE(bufoff, gbase, voff) do { _Pragma("unroll") for (int _i = 0; _i < 2; ++_i) \
;         __builtin_amdgcn_global_load_lds((const unsigned*)((const char*)(gbase) + (voff)[_i]), (PG8_LAS unsigned*)(lds + (bufoff) + ldsw + _i * 8192), 16, 0, 0); } while (0)
; #define PG8_LDA(dst, b, h) do { _Pragma("unroll") for (int m = 0; m < 4; ++m) _Pragma("unroll") for (int k = 0; k < 2; ++k) dst[m][k] = *(const PG8_LAS bf16x8*)(lds + PG8_SA(b, h) + aoff + m * 2048 + k * 1024); } while (0)
; #define PG8_MMA(ai, bj, At, Bt) do { __builtin_amdgcn_s_setprio(1); _Pragma("unroll") for (int m = 0; m < 4; ++m) _Pragma("unroll") for (int n = 0; n < 2; ++n) _Pragma("unroll") for (int k = 0; k < 2; ++k) \
;         acc[ai][bj][m][n] = __builtin_amdgcn_mfma_f32_16x16x32_bf16(Bt[n][k], At[m][k], acc[ai][bj][m][n], 0, 0, 0); __builtin_amdgcn_s_setprio(0); } while (0)
; #define PG8_WAIT_V(n) asm volatile("s_waitcnt vmcnt(" #n ")" ::: "memory")
; #define PG8_WAIT_L(n) asm volatile("s_waitcnt lgkmcnt(" #n ")" ::: "memory")
; #define PG8_BAR __builtin_amdgcn_s_barrier()
; #define PG8_SCHED __builtin_amdgcn_sched_barrier(0)
; template <class Epi, class Sched, bool ALIGN_EPI = false, bool SP2 = false>
; __device__ __forceinline__ void gemm_phase(PG8_LAS unsigned char* lds, const Gemm g, const Sched& S, const Epi& E) {
;     ...
;             PG8_LDA(At, 1, 1); PG8_STAGE(PG8_SB(1, 0), b3, voffB); PG8_STAGE(PG8_SB(1, 1), b3 + hstep, voffB); PG8_STAGE(PG8_SA(1, 0), a3, voffA);
;             PG8_WAIT_V(8); PG8_WAIT_L(0); PG8_BAR; PG8_MMA(1, 0, At, B0); PG8_MMA(1, 1, At, B1); PG8_BAR; PG8_SCHED;
;     ...
;         if constexpr (ALIGN_EPI) { if (wr == 0) PG8_BAR; }
	s_add_i32 s33, s33, s61
	v_lshl_add_u64 v[192:193], v[192:193], 0, s[92:93]
	s_mov_b32 m0, s33
	ds_read_b128 v[188:191], v194 offset:49152
	ds_read_b128 v[196:199], v194 offset:50176
	ds_read_b128 v[200:203], v194 offset:51200
	ds_read_b128 v[206:209], v194 offset:52224
	ds_read_b128 v[210:213], v194 offset:53248
	ds_read_b128 v[214:217], v194 offset:54272
	ds_read_b128 v[218:221], v194 offset:55296
	ds_read_b128 v[222:225], v194 offset:56320
	global_load_lds_dwordx4 v[192:193], off
	s_add_i32 m0, s33, 0x2000
	s_add_u32 s44, s44, 0x80080
	v_lshl_add_u64 v[192:193], v[226:227], 0, s[92:93]
	s_addc_u32 s45, s45, 0
	s_add_i32 s33, s50, s61
	global_load_lds_dwordx4 v[192:193], off
	v_lshl_add_u64 v[192:193], s[44:45], 0, v[146:147]
	s_mov_b32 m0, s33
	s_nop 0
	global_load_lds_dwordx4 v146, s[44:45]
	v_lshl_add_u64 v[192:193], s[44:45], 0, v[150:151]
	s_add_i32 m0, s33, 0x2000
	s_nop 0
	global_load_lds_dwordx4 v150, s[44:45]
	v_lshl_add_u64 v[192:193], v[228:229], 0, s[92:93]
	s_mov_b32 m0, s68
	s_nop 0
	global_load_lds_dwordx4 v[192:193], off
	v_lshl_add_u64 v[192:193], v[230:231], 0, s[92:93]
	s_mov_b32 m0, s69
	s_nop 0
	global_load_lds_dwordx4 v[192:193], off
	s_waitcnt vmcnt(8)
	s_waitcnt lgkmcnt(0)
	s_barrier
	s_setprio 1
	s_waitcnt lgkmcnt(0)
	v_mfma_f32_16x16x32_bf16 v[34:37], v[134:137], v[188:191], v[34:37]
	v_mfma_f32_16x16x32_bf16 v[30:33], v[142:145], v[188:191], v[30:33]
	v_mfma_f32_16x16x32_bf16 v[26:29], v[134:137], v[200:203], v[26:29]
	v_mfma_f32_16x16x32_bf16 v[22:25], v[142:145], v[200:203], v[22:25]
	v_mfma_f32_16x16x32_bf16 v[18:21], v[134:137], v[210:213], v[18:21]
	v_mfma_f32_16x16x32_bf16 v[10:13], v[142:145], v[210:213], v[10:13]
	v_mfma_f32_16x16x32_bf16 v[6:9], v[134:137], v[218:221], v[6:9]
	v_mfma_f32_16x16x32_bf16 v[2:5], v[142:145], v[218:221], v[2:5]
	v_mfma_f32_16x16x32_bf16 v[34:37], v[138:141], v[196:199], v[34:37]
	v_mfma_f32_16x16x32_bf16 v[30:33], v[168:171], v[196:199], v[30:33]
	v_mfma_f32_16x16x32_bf16 v[26:29], v[138:141], v[206:209], v[26:29]
	v_mfma_f32_16x16x32_bf16 v[22:25], v[168:171], v[206:209], v[22:25]
	v_mfma_f32_16x16x32_bf16 v[18:21], v[138:141], v[214:217], v[18:21]
	v_mfma_f32_16x16x32_bf16 v[10:13], v[168:171], v[214:217], v[10:13]
	v_mfma_f32_16x16x32_bf16 v[6:9], v[138:141], v[222:225], v[6:9]
	v_mfma_f32_16x16x32_bf16 v[2:5], v[168:171], v[222:225], v[2:5]
	s_setprio 0
	s_setprio 1
	v_mfma_f32_16x16x32_bf16 v[98:101], v[172:175], v[188:191], v[98:101]
	v_mfma_f32_16x16x32_bf16 v[94:97], v[180:183], v[188:191], v[94:97]
	v_mfma_f32_16x16x32_bf16 v[90:93], v[172:175], v[200:203], v[90:93]
	v_mfma_f32_16x16x32_bf16 v[86:89], v[180:183], v[200:203], v[86:89]
	v_mfma_f32_16x16x32_bf16 v[82:85], v[172:175], v[210:213], v[82:85]
	v_mfma_f32_16x16x32_bf16 v[78:81], v[180:183], v[210:213], v[78:81]
	v_mfma_f32_16x16x32_bf16 v[70:73], v[172:175], v[218:221], v[70:73]
	v_mfma_f32_16x16x32_bf16 v[66:69], v[180:183], v[218:221], v[66:69]
	v_mfma_f32_16x16x32_bf16 v[98:101], v[176:179], v[196:199], v[98:101]
	v_mfma_f32_16x16x32_bf16 v[94:97], v[184:187], v[196:199], v[94:97]
	v_mfma_f32_16x16x32_bf16 v[90:93], v[176:179], v[206:209], v[90:93]
	v_mfma_f32_16x16x32_bf16 v[86:89], v[184:187], v[206:209], v[86:89]
	v_mfma_f32_16x16x32_bf16 v[82:85], v[176:179], v[214:217], v[82:85]
	v_mfma_f32_16x16x32_bf16 v[78:81], v[184:187], v[214:217], v[78:81]
	v_mfma_f32_16x16x32_bf16 v[70:73], v[176:179], v[222:225], v[70:73]
	v_mfma_f32_16x16x32_bf16 v[66:69], v[184:187], v[222:225], v[66:69]
	s_setprio 0
	s_barrier
	s_add_i32 s49, s49, 2
	s_add_u32 s43, s43, 0x100
	s_addc_u32 s48, s48, 0
	s_add_u32 s40, s40, 0x100
	s_addc_u32 s41, s41, 0
	s_cmp_gt_u32 s49, 29
	s_cbranch_scc0 .LBB0_588
	s_and_b64 vcc, exec, s[18:19]
	s_cbranch_vccz .LBB0_591
	s_barrier

; #define PG8_STAGE(bufoff, gbase, voff) do { _Pragma("unroll") for (int _i = 0; _i < 2; ++_i) \
;         __builtin_amdgcn_global_load_lds((const unsigned*)((const char*)(gbase) + (voff)[_i]), (PG8_LAS unsigned*)(lds + (bufoff) + ldsw + _i * 8192), 16, 0, 0); } while (0)
; #define PG8_LDA(dst, b, h) do { _Pragma("unroll") for (int m = 0; m < 4; ++m) _Pragma("unroll") for (int k = 0; k < 2; ++k) dst[m][k] = *(const PG8_LAS bf16x8*)(lds + PG8_SA(b, h) + aoff + m * 2048 + k * 1024); } while (0)
; #define PG8_LDB(dst, b, h) do { _Pragma("unroll") for (int n = 0; n < 2; ++n) _Pragma("unroll") for (int k = 0; k < 2; ++k) dst[n][k] = *(const PG8_LAS bf16x8*)(lds + PG8_SB(b, h) + boff + n * 2048 + k * 1024); } while (0)
; #define PG8_MMA(ai, bj, At, Bt) do { __builtin_amdgcn_s_setprio(1); _Pragma("unroll") for (int m = 0; m < 4; ++m) _Pragma("unroll") for (int n = 0; n < 2; ++n) _Pragma("unroll") for (int k = 0; k < 2; ++k) \
;         acc[ai][bj][m][n] = __builtin_amdgcn_mfma_f32_16x16x32_bf16(Bt[n][k], At[m][k], acc[ai][bj][m][n], 0, 0, 0); __builtin_amdgcn_s_setprio(0); } while (0)
; #define PG8_WAIT_V(n) asm volatile("s_waitcnt vmcnt(" #n ")" ::: "memory")
; #define PG8_WAIT_L(n) asm volatile("s_waitcnt lgkmcnt(" #n ")" ::: "memory")
; template <class Epi, class Sched, bool ALIGN_EPI = false, bool SP2 = false>
; __device__ __forceinline__ void gemm_phase(PG8_LAS unsigned char* lds, const Gemm g, const Sched& S, const Epi& E) {
;     ...
;         for (int t = 0; t < nt; t += 2) {
;             const bool last = (t == nt - 2);
;             const char* a1 = cA + (size_t)(t + 1) * kstep;
;             const char* a2 = last ? nA : cA + (size_t)(t + 2) * kstep; const char* b2 = last ? nB : cB + (size_t)(t + 2) * kstep;
;             const char* a3 = a2 + kstep; const char* b3 = b2 + kstep;
;             if (last && has_next) S.a_ready(nxt);
;             if constexpr (Epi::MID) { if (t == nt / 2) E.mid(acc, cur, wr, wc, fr, fq); }
;             if constexpr (SP2) {
;             PG8_LDB(B0, 0, 0); PG8_LDB(B1, 0, 1); PG8_SCHED; PG8_LDA(At, 0, 0); PG8_STAGE(PG8_SA(1, 1), a1 + hstep, voffA);
;             PG8_WAIT_V(8); PG8_WAIT_L(0); PG8_BAR; PG8_MMA(0, 0, At, B0); PG8_MMA(0, 1, At, B1); PG8_BAR; PG8_SCHED;
;             PG8_LDA(At, 0, 1); PG8_STAGE(PG8_SB(0, 0), b2, voffB); PG8_STAGE(PG8_SB(0, 1), b2 + hstep, voffB); PG8_STAGE(PG8_SA(0, 0), a2, voffA);
.LBB0_1091:
	s_add_u32 s6, s30, s34
	s_addc_u32 s7, s31, s35
	s_add_u32 s6, s6, 0x100
	s_addc_u32 s7, s7, 0
	s_add_u32 s33, s59, s34
	s_addc_u32 s62, s60, s35
	s_cmpk_eq_i32 s34, 0xf00
	s_cselect_b32 s37, s55, s7
	s_cselect_b32 s36, s56, s6
	s_cselect_b32 s7, s57, s62
	s_cselect_b32 s6, s58, s33
	s_add_i32 s33, 0, 0x10000
	v_add_u32_e32 v0, s33, v249
	s_add_i32 s64, 0, 0x14000
	ds_read_b128 v[134:137], v0
	ds_read_b128 v[138:141], v0 offset:1024
	ds_read_b128 v[142:145], v0 offset:2048
	ds_read_b128 v[146:149], v0 offset:3072
	v_add_u32_e32 v0, s64, v249
	ds_read_b128 v[150:153], v0
	ds_read_b128 v[154:157], v0 offset:1024
	ds_read_b128 v[158:161], v0 offset:2048
	ds_read_b128 v[162:165], v0 offset:3072
	v_lshl_add_u64 v[2:3], v[172:173], 0, s[34:35]
	s_add_i32 m0, s15, 0xc000
	ds_read_b128 v[176:179], v202
	ds_read_b128 v[180:183], v202 offset:1024
	ds_read_b128 v[184:187], v202 offset:2048
	ds_read_b128 v[188:191], v202 offset:3072
	ds_read_b128 v[192:195], v202 offset:4096
	ds_read_b128 v[218:221], v202 offset:5120
	ds_read_b128 v[222:225], v202 offset:6144
	ds_read_b128 v[226:229], v202 offset:7168
	global_load_lds_dwordx4 v[2:3], off
	v_lshl_add_u64 v[2:3], v[170:171], 0, s[34:35]
	s_add_i32 m0, s15, 0xe000
	s_nop 0
	global_load_lds_dwordx4 v[2:3], off
	s_waitcnt vmcnt(8)
	s_waitcnt lgkmcnt(0)
	s_barrier
	s_setprio 1
	s_waitcnt lgkmcnt(0)
	v_mfma_f32_16x16x32_bf16 v[130:133], v[134:137], v[176:179], v[130:133]
	v_mfma_f32_16x16x32_bf16 v[126:129], v[142:145], v[176:179], v[126:129]
	v_mfma_f32_16x16x32_bf16 v[114:117], v[134:137], v[184:187], v[114:117]
	v_mfma_f32_16x16x32_bf16 v[110:113], v[142:145], v[184:187], v[110:113]
	v_mfma_f32_16x16x32_bf16 v[98:101], v[134:137], v[192:195], v[98:101]
	v_mfma_f32_16x16x32_bf16 v[94:97], v[142:145], v[192:195], v[94:97]
	v_mfma_f32_16x16x32_bf16 v[82:85], v[134:137], v[222:225], v[82:85]
	v_mfma_f32_16x16x32_bf16 v[78:81], v[142:145], v[222:225], v[78:81]
	v_mfma_f32_16x16x32_bf16 v[130:133], v[138:141], v[180:183], v[130:133]
	v_mfma_f32_16x16x32_bf16 v[126:129], v[146:149], v[180:183], v[126:129]
	v_mfma_f32_16x16x32_bf16 v[114:117], v[138:141], v[188:191], v[114:117]
	v_mfma_f32_16x16x32_bf16 v[110:113], v[146:149], v[188:191], v[110:113]
	v_mfma_f32_16x16x32_bf16 v[98:101], v[138:141], v[218:221], v[98:101]
	v_mfma_f32_16x16x32_bf16 v[94:97], v[146:149], v[218:221], v[94:97]
	v_mfma_f32_16x16x32_bf16 v[82:85], v[138:141], v[226:229], v[82:85]
	v_mfma_f32_16x16x32_bf16 v[78:81], v[146:149], v[226:229], v[78:81]
	s_setprio 0
	s_setprio 1
	v_mfma_f32_16x16x32_bf16 v[122:125], v[150:153], v[176:179], v[122:125]
	v_mfma_f32_16x16x32_bf16 v[118:121], v[158:161], v[176:179], v[118:121]
	v_mfma_f32_16x16x32_bf16 v[106:109], v[150:153], v[184:187], v[106:109]
	v_mfma_f32_16x16x32_bf16 v[102:105], v[158:161], v[184:187], v[102:105]
	v_mfma_f32_16x16x32_bf16 v[90:93], v[150:153], v[192:195], v[90:93]
	v_mfma_f32_16x16x32_bf16 v[86:89], v[158:161], v[192:195], v[86:89]
	v_mfma_f32_16x16x32_bf16 v[74:77], v[150:153], v[222:225], v[74:77]
	v_mfma_f32_16x16x32_bf16 v[70:73], v[158:161], v[222:225], v[70:73]
	v_mfma_f32_16x16x32_bf16 v[122:125], v[154:157], v[180:183], v[122:125]
	v_mfma_f32_16x16x32_bf16 v[118:121], v[162:165], v[180:183], v[118:121]
	v_mfma_f32_16x16x32_bf16 v[106:109], v[154:157], v[188:191], v[106:109]
	v_mfma_f32_16x16x32_bf16 v[102:105], v[162:165], v[188:191], v[102:105]
	v_mfma_f32_16x16x32_bf16 v[90:93], v[154:157], v[218:221], v[90:93]
	v_mfma_f32_16x16x32_bf16 v[86:89], v[162:165], v[218:221], v[86:89]
	v_mfma_f32_16x16x32_bf16 v[74:77], v[154:157], v[226:229], v[74:77]
	v_mfma_f32_16x16x32_bf16 v[70:73], v[162:165], v[226:229], v[70:73]
	s_setprio 0
	s_barrier
	s_add_i32 s33, s33, s43
	v_lshl_add_u64 v[196:197], s[6:7], 0, v[208:209]
	s_mov_b32 m0, s33
	ds_read_b128 v[176:179], v202 offset:16384
	ds_read_b128 v[180:183], v202 offset:17408
	ds_read_b128 v[184:187], v202 offset:18432
	ds_read_b128 v[188:191], v202 offset:19456
	ds_read_b128 v[192:195], v202 offset:20480
	ds_read_b128 v[218:221], v202 offset:21504
	ds_read_b128 v[222:225], v202 offset:22528
	ds_read_b128 v[226:229], v202 offset:23552
	global_load_lds_dwordx4 v208, s[6:7]
	s_add_i32 m0, s33, 0x2000
	s_add_u32 s62, s6, 0x80000
	v_lshl_add_u64 v[230:231], s[6:7], 0, v[212:213]
	s_addc_u32 s63, s7, 0
	s_add_i32 s33, s64, s43
	global_load_lds_dwordx4 v212, s[6:7]
	v_lshl_add_u64 v[2:3], s[62:63], 0, v[208:209]
	s_mov_b32 m0, s33
	v_lshl_add_u64 v[232:233], s[36:37], 0, v[206:207]
	global_load_lds_dwordx4 v208, s[62:63]
	v_lshl_add_u64 v[2:3], s[62:63], 0, v[212:213]
	s_add_i32 m0, s33, 0x2000
	v_lshl_add_u64 v[234:235], s[36:37], 0, v[210:211]
	global_load_lds_dwordx4 v212, s[62:63]
	s_mov_b32 m0, s15
	s_nop 0
	global_load_lds_dwordx4 v206, s[36:37]
	s_mov_b32 m0, s44
	s_nop 0
	global_load_lds_dwordx4 v210, s[36:37]
	s_waitcnt vmcnt(8)
	s_waitcnt lgkmcnt(0)
	s_barrier
; #define PG8_STAGE(bufoff, gbase, voff) do { _Pragma("unroll") for (int _i = 0; _i < 2; ++_i) \
;         __builtin_amdgcn_global_load_lds((const unsigned*)((const char*)(gbase) + (voff)[_i]), (PG8_LAS unsigned*)(lds + (bufoff) + ldsw + _i * 8192), 16, 0, 0); } while (0)
; #define PG8_LDA(dst, b, h) do { _Pragma("unroll") for (int m = 0; m < 4; ++m) _Pragma("unroll") for (int k = 0; k < 2; ++k) dst[m][k] = *(const PG8_LAS bf16x8*)(lds + PG8_SA(b, h) + aoff + m * 2048 + k * 1024); } while (0)
; #define PG8_LDB(dst, b, h) do { _Pragma("unroll") for (int n = 0; n < 2; ++n) _Pragma("unroll") for (int k = 0; k < 2; ++k) dst[n][k] = *(const PG8_LAS bf16x8*)(lds + PG8_SB(b, h) + boff + n * 2048 + k * 1024); } while (0)
; #define PG8_MMA(ai, bj, At, Bt) do { __builtin_amdgcn_s_setprio(1); _Pragma("unroll") for (int m = 0; m < 4; ++m) _Pragma("unroll") for (int n = 0; n < 2; ++n) _Pragma("unroll") for (int k = 0; k < 2; ++k) \
;         acc[ai][bj][m][n] = __builtin_amdgcn_mfma_f32_16x16x32_bf16(Bt[n][k], At[m][k], acc[ai][bj][m][n], 0, 0, 0); __builtin_amdgcn_s_setprio(0); } while (0)
; #define PG8_WAIT_V(n) asm volatile("s_waitcnt vmcnt(" #n ")" ::: "memory")
; #define PG8_WAIT_L(n) asm volatile("s_waitcnt lgkmcnt(" #n ")" ::: "memory")
; #define PG8_BAR __builtin_amdgcn_s_barrier()
; #define PG8_SCHED __builtin_amdgcn_sched_barrier(0)
; template <class Epi, class Sched, bool ALIGN_EPI = false, bool SP2 = false>
; __device__ __forceinline__ void gemm_phase(PG8_LAS unsigned char* lds, const Gemm g, const Sched& S, const Epi& E) {
;     ...
;             PG8_WAIT_V(8); PG8_WAIT_L(0); PG8_BAR; PG8_MMA(1, 0, At, B0); PG8_MMA(1, 1, At, B1); PG8_BAR; PG8_SCHED;
;             PG8_LDB(B0, 1, 0); PG8_LDB(B1, 1, 1); PG8_SCHED; PG8_LDA(At, 1, 0); PG8_STAGE(PG8_SA(0, 1), a2 + hstep, voffA);
;             PG8_WAIT_V(8); PG8_WAIT_L(0); PG8_BAR; PG8_MMA(0, 0, At, B0); PG8_MMA(0, 1, At, B1); PG8_BAR; PG8_SCHED;
	s_setprio 1
	s_waitcnt lgkmcnt(0)
	v_mfma_f32_16x16x32_bf16 v[66:69], v[134:137], v[176:179], v[66:69]
	v_mfma_f32_16x16x32_bf16 v[62:65], v[142:145], v[176:179], v[62:65]
	v_mfma_f32_16x16x32_bf16 v[50:53], v[134:137], v[184:187], v[50:53]
	v_mfma_f32_16x16x32_bf16 v[46:49], v[142:145], v[184:187], v[46:49]
	v_mfma_f32_16x16x32_bf16 v[34:37], v[134:137], v[192:195], v[34:37]
	v_mfma_f32_16x16x32_bf16 v[30:33], v[142:145], v[192:195], v[30:33]
	v_mfma_f32_16x16x32_bf16 v[18:21], v[134:137], v[222:225], v[18:21]
	v_mfma_f32_16x16x32_bf16 v[12:15], v[142:145], v[222:225], v[12:15]
	v_mfma_f32_16x16x32_bf16 v[66:69], v[138:141], v[180:183], v[66:69]
	v_mfma_f32_16x16x32_bf16 v[62:65], v[146:149], v[180:183], v[62:65]
	v_mfma_f32_16x16x32_bf16 v[50:53], v[138:141], v[188:191], v[50:53]
	v_mfma_f32_16x16x32_bf16 v[46:49], v[146:149], v[188:191], v[46:49]
	v_mfma_f32_16x16x32_bf16 v[34:37], v[138:141], v[218:221], v[34:37]
	v_mfma_f32_16x16x32_bf16 v[30:33], v[146:149], v[218:221], v[30:33]
	v_mfma_f32_16x16x32_bf16 v[18:21], v[138:141], v[226:229], v[18:21]
	v_mfma_f32_16x16x32_bf16 v[12:15], v[146:149], v[226:229], v[12:15]
	s_setprio 0
	s_setprio 1
	v_mfma_f32_16x16x32_bf16 v[58:61], v[150:153], v[176:179], v[58:61]
	v_mfma_f32_16x16x32_bf16 v[54:57], v[158:161], v[176:179], v[54:57]
	v_mfma_f32_16x16x32_bf16 v[42:45], v[150:153], v[184:187], v[42:45]
	v_mfma_f32_16x16x32_bf16 v[38:41], v[158:161], v[184:187], v[38:41]
	v_mfma_f32_16x16x32_bf16 v[26:29], v[150:153], v[192:195], v[26:29]
	v_mfma_f32_16x16x32_bf16 v[22:25], v[158:161], v[192:195], v[22:25]
	v_mfma_f32_16x16x32_bf16 v[8:11], v[150:153], v[222:225], v[8:11]
	v_mfma_f32_16x16x32_bf16 v[2:5], v[158:161], v[222:225], v[4:7]
	v_mfma_f32_16x16x32_bf16 v[58:61], v[154:157], v[180:183], v[58:61]
	v_mfma_f32_16x16x32_bf16 v[54:57], v[162:165], v[180:183], v[54:57]
	v_mfma_f32_16x16x32_bf16 v[42:45], v[154:157], v[188:191], v[42:45]
	v_mfma_f32_16x16x32_bf16 v[38:41], v[162:165], v[188:191], v[38:41]
	v_mfma_f32_16x16x32_bf16 v[26:29], v[154:157], v[218:221], v[26:29]
	v_mfma_f32_16x16x32_bf16 v[22:25], v[162:165], v[218:221], v[22:25]
	v_mfma_f32_16x16x32_bf16 v[8:11], v[154:157], v[226:229], v[8:11]
	v_mfma_f32_16x16x32_bf16 v[2:5], v[162:165], v[226:229], v[2:5]
	s_setprio 0
	s_barrier
	s_add_i32 s33, 0, 0x18000
	v_add_u32_e32 v0, s33, v249
	s_add_i32 s62, 0, 0x1c000
	ds_read_b128 v[134:137], v0
	ds_read_b128 v[138:141], v0 offset:1024
	ds_read_b128 v[142:145], v0 offset:2048
	ds_read_b128 v[146:149], v0 offset:3072
	v_add_u32_e32 v0, s62, v249
	ds_read_b128 v[150:153], v0
	ds_read_b128 v[154:157], v0 offset:1024
	ds_read_b128 v[158:161], v0 offset:2048
	ds_read_b128 v[162:165], v0 offset:3072
	s_add_u32 s36, s36, 0x80000
	s_addc_u32 s37, s37, 0
	s_mov_b32 m0, s45
	v_lshl_add_u64 v[6:7], s[36:37], 0, v[206:207]
	ds_read_b128 v[176:179], v202 offset:32768
	ds_read_b128 v[180:183], v202 offset:33792
	ds_read_b128 v[184:187], v202 offset:34816
	ds_read_b128 v[188:191], v202 offset:35840
	ds_read_b128 v[192:195], v202 offset:36864
	ds_read_b128 v[218:221], v202 offset:37888
	ds_read_b128 v[222:225], v202 offset:38912
	ds_read_b128 v[226:229], v202 offset:39936
	global_load_lds_dwordx4 v206, s[36:37]
	v_lshl_add_u64 v[6:7], s[36:37], 0, v[210:211]
	s_mov_b32 m0, s46
	s_nop 0
	global_load_lds_dwordx4 v210, s[36:37]
	s_waitcnt vmcnt(8)
	s_waitcnt lgkmcnt(0)
	s_barrier
	s_setprio 1
	s_waitcnt lgkmcnt(0)
	v_mfma_f32_16x16x32_bf16 v[130:133], v[134:137], v[176:179], v[130:133]
	v_mfma_f32_16x16x32_bf16 v[126:129], v[142:145], v[176:179], v[126:129]
	v_mfma_f32_16x16x32_bf16 v[114:117], v[134:137], v[184:187], v[114:117]
	v_mfma_f32_16x16x32_bf16 v[110:113], v[142:145], v[184:187], v[110:113]
	v_mfma_f32_16x16x32_bf16 v[98:101], v[134:137], v[192:195], v[98:101]
	v_mfma_f32_16x16x32_bf16 v[94:97], v[142:145], v[192:195], v[94:97]
	v_mfma_f32_16x16x32_bf16 v[82:85], v[134:137], v[222:225], v[82:85]
	v_mfma_f32_16x16x32_bf16 v[78:81], v[142:145], v[222:225], v[78:81]
	v_mfma_f32_16x16x32_bf16 v[130:133], v[138:141], v[180:183], v[130:133]
	v_mfma_f32_16x16x32_bf16 v[126:129], v[146:149], v[180:183], v[126:129]
	v_mfma_f32_16x16x32_bf16 v[114:117], v[138:141], v[188:191], v[114:117]
	v_mfma_f32_16x16x32_bf16 v[110:113], v[146:149], v[188:191], v[110:113]
	v_mfma_f32_16x16x32_bf16 v[98:101], v[138:141], v[218:221], v[98:101]
	v_mfma_f32_16x16x32_bf16 v[94:97], v[146:149], v[218:221], v[94:97]
	v_mfma_f32_16x16x32_bf16 v[82:85], v[138:141], v[226:229], v[82:85]
	v_mfma_f32_16x16x32_bf16 v[78:81], v[146:149], v[226:229], v[78:81]
	s_setprio 0
	s_setprio 1
	v_mfma_f32_16x16x32_bf16 v[122:125], v[150:153], v[176:179], v[122:125]
	v_mfma_f32_16x16x32_bf16 v[118:121], v[158:161], v[176:179], v[118:121]
	v_mfma_f32_16x16x32_bf16 v[106:109], v[150:153], v[184:187], v[106:109]
	v_mfma_f32_16x16x32_bf16 v[102:105], v[158:161], v[184:187], v[102:105]
	v_mfma_f32_16x16x32_bf16 v[90:93], v[150:153], v[192:195], v[90:93]
	v_mfma_f32_16x16x32_bf16 v[86:89], v[158:161], v[192:195], v[86:89]
	v_mfma_f32_16x16x32_bf16 v[74:77], v[150:153], v[222:225], v[74:77]
	v_mfma_f32_16x16x32_bf16 v[70:73], v[158:161], v[222:225], v[70:73]
	v_mfma_f32_16x16x32_bf16 v[122:125], v[154:157], v[180:183], v[122:125]
	v_mfma_f32_16x16x32_bf16 v[118:121], v[162:165], v[180:183], v[118:121]
	v_mfma_f32_16x16x32_bf16 v[106:109], v[154:157], v[188:191], v[106:109]
	v_mfma_f32_16x16x32_bf16 v[102:105], v[162:165], v[188:191], v[102:105]
	v_mfma_f32_16x16x32_bf16 v[90:93], v[154:157], v[218:221], v[90:93]
	v_mfma_f32_16x16x32_bf16 v[86:89], v[162:165], v[218:221], v[86:89]
	v_mfma_f32_16x16x32_bf16 v[74:77], v[154:157], v[226:229], v[74:77]
	v_mfma_f32_16x16x32_bf16 v[70:73], v[162:165], v[226:229], v[70:73]
	s_setprio 0
	s_barrier
; #define PG8_STAGE(bufoff, gbase, voff) do { _Pragma("unroll") for (int _i = 0; _i < 2; ++_i) \
;         __builtin_amdgcn_global_load_lds((const unsigned*)((const char*)(gbase) + (voff)[_i]), (PG8_LAS unsigned*)(lds + (bufoff) + ldsw + _i * 8192), 16, 0, 0); } while (0)
; #define PG8_LDA(dst, b, h) do { _Pragma("unroll") for (int m = 0; m < 4; ++m) _Pragma("unroll") for (int k = 0; k < 2; ++k) dst[m][k] = *(const PG8_LAS bf16x8*)(lds + PG8_SA(b, h) + aoff + m * 2048 + k * 1024); } while (0)
; #define PG8_MMA(ai, bj, At, Bt) do { __builtin_amdgcn_s_setprio(1); _Pragma("unroll") for (int m = 0; m < 4; ++m) _Pragma("unroll") for (int n = 0; n < 2; ++n) _Pragma("unroll") for (int k = 0; k < 2; ++k) \
;         acc[ai][bj][m][n] = __builtin_amdgcn_mfma_f32_16x16x32_bf16(Bt[n][k], At[m][k], acc[ai][bj][m][n], 0, 0, 0); __builtin_amdgcn_s_setprio(0); } while (0)
; #define PG8_WAIT_V(n) asm volatile("s_waitcnt vmcnt(" #n ")" ::: "memory")
; #define PG8_WAIT_L(n) asm volatile("s_waitcnt lgkmcnt(" #n ")" ::: "memory")
; #define PG8_BAR __builtin_amdgcn_s_barrier()
; #define PG8_SCHED __builtin_amdgcn_sched_barrier(0)
; template <class Epi, class Sched, bool ALIGN_EPI = false, bool SP2 = false>
; __device__ __forceinline__ void gemm_phase(PG8_LAS unsigned char* lds, const Gemm g, const Sched& S, const Epi& E) {
;     ...
;             PG8_LDA(At, 1, 1); PG8_STAGE(PG8_SB(1, 0), b3, voffB); PG8_STAGE(PG8_SB(1, 1), b3 + hstep, voffB); PG8_STAGE(PG8_SA(1, 0), a3, voffA);
;             PG8_WAIT_V(8); PG8_WAIT_L(0); PG8_BAR; PG8_MMA(1, 0, At, B0); PG8_MMA(1, 1, At, B1); PG8_BAR; PG8_SCHED;
	s_add_i32 s33, s33, s43
	v_lshl_add_u64 v[6:7], v[196:197], 0, s[92:93]
	s_mov_b32 m0, s33
	ds_read_b128 v[176:179], v202 offset:49152
	ds_read_b128 v[180:183], v202 offset:50176
	ds_read_b128 v[184:187], v202 offset:51200
	ds_read_b128 v[188:191], v202 offset:52224
	ds_read_b128 v[192:195], v202 offset:53248
	ds_read_b128 v[218:221], v202 offset:54272
	ds_read_b128 v[222:225], v202 offset:55296
	ds_read_b128 v[226:229], v202 offset:56320
	global_load_lds_dwordx4 v[6:7], off
	s_add_i32 m0, s33, 0x2000
	s_add_u32 s6, s6, 0x80080
	v_lshl_add_u64 v[6:7], v[230:231], 0, s[92:93]
	s_addc_u32 s7, s7, 0
	s_add_i32 s33, s62, s43
	global_load_lds_dwordx4 v[6:7], off
	v_lshl_add_u64 v[6:7], s[6:7], 0, v[208:209]
	s_mov_b32 m0, s33
	s_nop 0
	global_load_lds_dwordx4 v208, s[6:7]
	v_lshl_add_u64 v[6:7], s[6:7], 0, v[212:213]
	s_add_i32 m0, s33, 0x2000
	s_nop 0
	global_load_lds_dwordx4 v212, s[6:7]
	v_lshl_add_u64 v[6:7], v[232:233], 0, s[92:93]
	s_mov_b32 m0, s48
	s_nop 0
	global_load_lds_dwordx4 v[6:7], off
	v_lshl_add_u64 v[6:7], v[234:235], 0, s[92:93]
	s_mov_b32 m0, s49
	s_nop 0
	global_load_lds_dwordx4 v[6:7], off
	s_waitcnt vmcnt(8)
	s_waitcnt lgkmcnt(0)
	s_barrier
	s_setprio 1
	s_waitcnt lgkmcnt(0)
	v_mfma_f32_16x16x32_bf16 v[66:69], v[134:137], v[176:179], v[66:69]
	v_mfma_f32_16x16x32_bf16 v[62:65], v[142:145], v[176:179], v[62:65]
	v_mfma_f32_16x16x32_bf16 v[50:53], v[134:137], v[184:187], v[50:53]
	v_mfma_f32_16x16x32_bf16 v[46:49], v[142:145], v[184:187], v[46:49]
	v_mfma_f32_16x16x32_bf16 v[34:37], v[134:137], v[192:195], v[34:37]
	v_mfma_f32_16x16x32_bf16 v[30:33], v[142:145], v[192:195], v[30:33]
	v_mfma_f32_16x16x32_bf16 v[18:21], v[134:137], v[222:225], v[18:21]
	v_mfma_f32_16x16x32_bf16 v[12:15], v[142:145], v[222:225], v[12:15]
	v_mfma_f32_16x16x32_bf16 v[66:69], v[138:141], v[180:183], v[66:69]
	v_mfma_f32_16x16x32_bf16 v[62:65], v[146:149], v[180:183], v[62:65]
	v_mfma_f32_16x16x32_bf16 v[50:53], v[138:141], v[188:191], v[50:53]
	v_mfma_f32_16x16x32_bf16 v[46:49], v[146:149], v[188:191], v[46:49]
	v_mfma_f32_16x16x32_bf16 v[34:37], v[138:141], v[218:221], v[34:37]
	v_mfma_f32_16x16x32_bf16 v[30:33], v[146:149], v[218:221], v[30:33]
	v_mfma_f32_16x16x32_bf16 v[18:21], v[138:141], v[226:229], v[18:21]
	v_mfma_f32_16x16x32_bf16 v[12:15], v[146:149], v[226:229], v[12:15]
	s_setprio 0
	s_setprio 1
	v_mfma_f32_16x16x32_bf16 v[58:61], v[150:153], v[176:179], v[58:61]
	v_mfma_f32_16x16x32_bf16 v[54:57], v[158:161], v[176:179], v[54:57]
	v_mfma_f32_16x16x32_bf16 v[42:45], v[150:153], v[184:187], v[42:45]
	v_mfma_f32_16x16x32_bf16 v[38:41], v[158:161], v[184:187], v[38:41]
	v_mfma_f32_16x16x32_bf16 v[26:29], v[150:153], v[192:195], v[26:29]
	v_mfma_f32_16x16x32_bf16 v[22:25], v[158:161], v[192:195], v[22:25]
	v_mfma_f32_16x16x32_bf16 v[6:9], v[150:153], v[222:225], v[8:11]
	v_mfma_f32_16x16x32_bf16 v[2:5], v[158:161], v[222:225], v[2:5]
	v_mfma_f32_16x16x32_bf16 v[58:61], v[154:157], v[180:183], v[58:61]
	v_mfma_f32_16x16x32_bf16 v[54:57], v[162:165], v[180:183], v[54:57]
	v_mfma_f32_16x16x32_bf16 v[42:45], v[154:157], v[188:191], v[42:45]
	v_mfma_f32_16x16x32_bf16 v[38:41], v[162:165], v[188:191], v[38:41]
	v_mfma_f32_16x16x32_bf16 v[26:29], v[154:157], v[218:221], v[26:29]
	v_mfma_f32_16x16x32_bf16 v[22:25], v[162:165], v[218:221], v[22:25]
	v_mfma_f32_16x16x32_bf16 v[8:11], v[154:157], v[226:229], v[6:9]
	v_mfma_f32_16x16x32_bf16 v[4:7], v[162:165], v[226:229], v[2:5]
	s_setprio 0
	s_barrier
	s_add_i32 s61, s61, 2
	s_add_u32 s34, s34, 0x100
	s_addc_u32 s35, s35, 0
	s_cmp_gt_u32 s61, 29
	s_cbranch_scc1 .LBB0_1096

; #define PG8_STAGE(bufoff, gbase, voff) do { _Pragma("unroll") for (int _i = 0; _i < 2; ++_i) \
;         __builtin_amdgcn_global_load_lds((const unsigned*)((const char*)(gbase) + (voff)[_i]), (PG8_LAS unsigned*)(lds + (bufoff) + ldsw + _i * 8192), 16, 0, 0); } while (0)
; #define PG8_LDA(dst, b, h) do { _Pragma("unroll") for (int m = 0; m < 4; ++m) _Pragma("unroll") for (int k = 0; k < 2; ++k) dst[m][k] = *(const PG8_LAS bf16x8*)(lds + PG8_SA(b, h) + aoff + m * 2048 + k * 1024); } while (0)
; #define PG8_LDB(dst, b, h) do { _Pragma("unroll") for (int n = 0; n < 2; ++n) _Pragma("unroll") for (int k = 0; k < 2; ++k) dst[n][k] = *(const PG8_LAS bf16x8*)(lds + PG8_SB(b, h) + boff + n * 2048 + k * 1024); } while (0)
; #define PG8_MMA(ai, bj, At, Bt) do { __builtin_amdgcn_s_setprio(1); _Pragma("unroll") for (int m = 0; m < 4; ++m) _Pragma("unroll") for (int n = 0; n < 2; ++n) _Pragma("unroll") for (int k = 0; k < 2; ++k) \
;         acc[ai][bj][m][n] = __builtin_amdgcn_mfma_f32_16x16x32_bf16(Bt[n][k], At[m][k], acc[ai][bj][m][n], 0, 0, 0); __builtin_amdgcn_s_setprio(0); } while (0)
; #define PG8_WAIT_V(n) asm volatile("s_waitcnt vmcnt(" #n ")" ::: "memory")
; #define PG8_WAIT_L(n) asm volatile("s_waitcnt lgkmcnt(" #n ")" ::: "memory")
; template <class Epi, class Sched, bool ALIGN_EPI = false, bool SP2 = false>
; __device__ __forceinline__ void gemm_phase(PG8_LAS unsigned char* lds, const Gemm g, const Sched& S, const Epi& E) {
;     ...
;         for (int t = 0; t < nt; t += 2) {
;             const bool last = (t == nt - 2);
;             const char* a1 = cA + (size_t)(t + 1) * kstep;
;             const char* a2 = last ? nA : cA + (size_t)(t + 2) * kstep; const char* b2 = last ? nB : cB + (size_t)(t + 2) * kstep;
;             const char* a3 = a2 + kstep; const char* b3 = b2 + kstep;
;             if (last && has_next) S.a_ready(nxt);
;             if constexpr (Epi::MID) { if (t == nt / 2) E.mid(acc, cur, wr, wc, fr, fq); }
;             if constexpr (SP2) {
;             PG8_LDB(B0, 0, 0); PG8_LDB(B1, 0, 1); PG8_SCHED; PG8_LDA(At, 0, 0); PG8_STAGE(PG8_SA(1, 1), a1 + hstep, voffA);
;             PG8_WAIT_V(8); PG8_WAIT_L(0); PG8_BAR; PG8_MMA(0, 0, At, B0); PG8_MMA(0, 1, At, B1); PG8_BAR; PG8_SCHED;
;             PG8_LDA(At, 0, 1); PG8_STAGE(PG8_SB(0, 0), b2, voffB); PG8_STAGE(PG8_SB(0, 1), b2 + hstep, voffB); PG8_STAGE(PG8_SA(0, 0), a2, voffA);
.LBB0_1223:
	s_add_u32 s28, s26, 0xfff80080
	s_addc_u32 s29, s27, -1
	s_add_i32 s33, 0, 0x10000
	s_cmp_eq_u32 s56, 28
	s_cselect_b32 s31, s5, s29
	s_cselect_b32 s30, s11, s28
	v_add_u32_e32 v161, s33, v155
	s_cselect_b32 s29, s19, s55
	s_cselect_b32 s28, s21, s54
	s_add_i32 s57, 0, 0x14000
	ds_read_b128 v[142:145], v161
	ds_read_b128 v[146:149], v161 offset:1024
	ds_read_b128 v[150:153], v161 offset:2048
	ds_read_b128 v[162:165], v161 offset:3072
	v_add_u32_e32 v161, s57, v155
	ds_read_b128 v[166:169], v161
	ds_read_b128 v[170:173], v161 offset:1024
	ds_read_b128 v[174:177], v161 offset:2048
	ds_read_b128 v[178:181], v161 offset:3072
	v_lshl_add_u64 v[202:203], s[26:27], 0, v[140:141]
	s_add_i32 m0, s42, 0xc000
	ds_read_b128 v[182:185], v160
	ds_read_b128 v[186:189], v160 offset:1024
	ds_read_b128 v[190:193], v160 offset:2048
	ds_read_b128 v[194:197], v160 offset:3072
	ds_read_b128 v[198:201], v160 offset:4096
	ds_read_b128 v[206:209], v160 offset:5120
	ds_read_b128 v[210:213], v160 offset:6144
	ds_read_b128 v[214:217], v160 offset:7168
	global_load_lds_dwordx4 v140, s[26:27]
	v_lshl_add_u64 v[202:203], s[26:27], 0, v[138:139]
	s_add_i32 m0, s42, 0xe000
	s_nop 0
	global_load_lds_dwordx4 v138, s[26:27]
	s_waitcnt vmcnt(8)
	s_waitcnt lgkmcnt(0)
	s_barrier
	s_setprio 1
	s_waitcnt lgkmcnt(0)
	v_mfma_f32_16x16x32_bf16 v[130:133], v[142:145], v[182:185], v[130:133]
	v_mfma_f32_16x16x32_bf16 v[126:129], v[150:153], v[182:185], v[126:129]
	v_mfma_f32_16x16x32_bf16 v[114:117], v[142:145], v[190:193], v[114:117]
	v_mfma_f32_16x16x32_bf16 v[110:113], v[150:153], v[190:193], v[110:113]
	v_mfma_f32_16x16x32_bf16 v[98:101], v[142:145], v[198:201], v[98:101]
	v_mfma_f32_16x16x32_bf16 v[94:97], v[150:153], v[198:201], v[94:97]
	v_mfma_f32_16x16x32_bf16 v[82:85], v[142:145], v[210:213], v[82:85]
	v_mfma_f32_16x16x32_bf16 v[78:81], v[150:153], v[210:213], v[78:81]
	v_mfma_f32_16x16x32_bf16 v[130:133], v[146:149], v[186:189], v[130:133]
	v_mfma_f32_16x16x32_bf16 v[126:129], v[162:165], v[186:189], v[126:129]
	v_mfma_f32_16x16x32_bf16 v[114:117], v[146:149], v[194:197], v[114:117]
	v_mfma_f32_16x16x32_bf16 v[110:113], v[162:165], v[194:197], v[110:113]
	v_mfma_f32_16x16x32_bf16 v[98:101], v[146:149], v[206:209], v[98:101]
	v_mfma_f32_16x16x32_bf16 v[94:97], v[162:165], v[206:209], v[94:97]
	v_mfma_f32_16x16x32_bf16 v[82:85], v[146:149], v[214:217], v[82:85]
	v_mfma_f32_16x16x32_bf16 v[78:81], v[162:165], v[214:217], v[78:81]
	s_setprio 0
	s_setprio 1
	v_mfma_f32_16x16x32_bf16 v[122:125], v[166:169], v[182:185], v[122:125]
	v_mfma_f32_16x16x32_bf16 v[118:121], v[174:177], v[182:185], v[118:121]
	v_mfma_f32_16x16x32_bf16 v[106:109], v[166:169], v[190:193], v[106:109]
	v_mfma_f32_16x16x32_bf16 v[102:105], v[174:177], v[190:193], v[102:105]
	v_mfma_f32_16x16x32_bf16 v[90:93], v[166:169], v[198:201], v[90:93]
	v_mfma_f32_16x16x32_bf16 v[86:89], v[174:177], v[198:201], v[86:89]
	v_mfma_f32_16x16x32_bf16 v[74:77], v[166:169], v[210:213], v[74:77]
	v_mfma_f32_16x16x32_bf16 v[70:73], v[174:177], v[210:213], v[70:73]
	v_mfma_f32_16x16x32_bf16 v[122:125], v[170:173], v[186:189], v[122:125]
	v_mfma_f32_16x16x32_bf16 v[118:121], v[178:181], v[186:189], v[118:121]
	v_mfma_f32_16x16x32_bf16 v[106:109], v[170:173], v[194:197], v[106:109]
	v_mfma_f32_16x16x32_bf16 v[102:105], v[178:181], v[194:197], v[102:105]
	v_mfma_f32_16x16x32_bf16 v[90:93], v[170:173], v[206:209], v[90:93]
	v_mfma_f32_16x16x32_bf16 v[86:89], v[178:181], v[206:209], v[86:89]
	v_mfma_f32_16x16x32_bf16 v[74:77], v[170:173], v[214:217], v[74:77]
	v_mfma_f32_16x16x32_bf16 v[70:73], v[178:181], v[214:217], v[70:73]
	s_setprio 0
	s_barrier
	s_add_i32 s33, s33, s40
	v_lshl_add_u64 v[202:203], s[28:29], 0, v[0:1]
	s_mov_b32 m0, s33
	ds_read_b128 v[182:185], v160 offset:16384
	ds_read_b128 v[186:189], v160 offset:17408
	ds_read_b128 v[190:193], v160 offset:18432
	ds_read_b128 v[194:197], v160 offset:19456
	ds_read_b128 v[198:201], v160 offset:20480
	ds_read_b128 v[206:209], v160 offset:21504
	ds_read_b128 v[210:213], v160 offset:22528
	ds_read_b128 v[214:217], v160 offset:23552
	global_load_lds_dwordx4 v0, s[28:29]
	s_add_i32 m0, s33, 0x2000
	s_add_u32 s58, s28, 0x80000
	v_lshl_add_u64 v[218:219], s[28:29], 0, v[14:15]
	s_addc_u32 s59, s29, 0
	s_add_i32 s33, s57, s40
	global_load_lds_dwordx4 v14, s[28:29]
	v_lshl_add_u64 v[220:221], s[58:59], 0, v[0:1]
	s_mov_b32 m0, s33
	v_lshl_add_u64 v[222:223], s[30:31], 0, v[134:135]
	global_load_lds_dwordx4 v0, s[58:59]
	v_lshl_add_u64 v[220:221], s[58:59], 0, v[14:15]
	s_add_i32 m0, s33, 0x2000
	s_nop 0
	global_load_lds_dwordx4 v14, s[58:59]
	v_lshl_add_u64 v[220:221], s[30:31], 0, v[136:137]
	s_mov_b32 m0, s42
	s_nop 0
	global_load_lds_dwordx4 v136, s[30:31]
	s_mov_b32 m0, s43
	s_nop 0
	global_load_lds_dwordx4 v134, s[30:31]
	s_waitcnt vmcnt(8)
	s_waitcnt lgkmcnt(0)
	s_barrier
; #define PG8_STAGE(bufoff, gbase, voff) do { _Pragma("unroll") for (int _i = 0; _i < 2; ++_i) \
;         __builtin_amdgcn_global_load_lds((const unsigned*)((const char*)(gbase) + (voff)[_i]), (PG8_LAS unsigned*)(lds + (bufoff) + ldsw + _i * 8192), 16, 0, 0); } while (0)
; #define PG8_LDA(dst, b, h) do { _Pragma("unroll") for (int m = 0; m < 4; ++m) _Pragma("unroll") for (int k = 0; k < 2; ++k) dst[m][k] = *(const PG8_LAS bf16x8*)(lds + PG8_SA(b, h) + aoff + m * 2048 + k * 1024); } while (0)
; #define PG8_LDB(dst, b, h) do { _Pragma("unroll") for (int n = 0; n < 2; ++n) _Pragma("unroll") for (int k = 0; k < 2; ++k) dst[n][k] = *(const PG8_LAS bf16x8*)(lds + PG8_SB(b, h) + boff + n * 2048 + k * 1024); } while (0)
; #define PG8_MMA(ai, bj, At, Bt) do { __builtin_amdgcn_s_setprio(1); _Pragma("unroll") for (int m = 0; m < 4; ++m) _Pragma("unroll") for (int n = 0; n < 2; ++n) _Pragma("unroll") for (int k = 0; k < 2; ++k) \
;         acc[ai][bj][m][n] = __builtin_amdgcn_mfma_f32_16x16x32_bf16(Bt[n][k], At[m][k], acc[ai][bj][m][n], 0, 0, 0); __builtin_amdgcn_s_setprio(0); } while (0)
; #define PG8_WAIT_V(n) asm volatile("s_waitcnt vmcnt(" #n ")" ::: "memory")
; #define PG8_WAIT_L(n) asm volatile("s_waitcnt lgkmcnt(" #n ")" ::: "memory")
; #define PG8_BAR __builtin_amdgcn_s_barrier()
; #define PG8_SCHED __builtin_amdgcn_sched_barrier(0)
; template <class Epi, class Sched, bool ALIGN_EPI = false, bool SP2 = false>
; __device__ __forceinline__ void gemm_phase(PG8_LAS unsigned char* lds, const Gemm g, const Sched& S, const Epi& E) {
;     ...
;             PG8_WAIT_V(8); PG8_WAIT_L(0); PG8_BAR; PG8_MMA(1, 0, At, B0); PG8_MMA(1, 1, At, B1); PG8_BAR; PG8_SCHED;
;             PG8_LDB(B0, 1, 0); PG8_LDB(B1, 1, 1); PG8_SCHED; PG8_LDA(At, 1, 0); PG8_STAGE(PG8_SA(0, 1), a2 + hstep, voffA);
;             PG8_WAIT_V(8); PG8_WAIT_L(0); PG8_BAR; PG8_MMA(0, 0, At, B0); PG8_MMA(0, 1, At, B1); PG8_BAR; PG8_SCHED;
	s_setprio 1
	s_waitcnt lgkmcnt(0)
	v_mfma_f32_16x16x32_bf16 v[66:69], v[142:145], v[182:185], v[66:69]
	v_mfma_f32_16x16x32_bf16 v[62:65], v[150:153], v[182:185], v[62:65]
	v_mfma_f32_16x16x32_bf16 v[50:53], v[142:145], v[190:193], v[50:53]
	v_mfma_f32_16x16x32_bf16 v[46:49], v[150:153], v[190:193], v[46:49]
	v_mfma_f32_16x16x32_bf16 v[34:37], v[142:145], v[198:201], v[34:37]
	v_mfma_f32_16x16x32_bf16 v[30:33], v[150:153], v[198:201], v[30:33]
	v_mfma_f32_16x16x32_bf16 v[18:21], v[142:145], v[210:213], v[18:21]
	v_mfma_f32_16x16x32_bf16 v[10:13], v[150:153], v[210:213], v[10:13]
	v_mfma_f32_16x16x32_bf16 v[66:69], v[146:149], v[186:189], v[66:69]
	v_mfma_f32_16x16x32_bf16 v[62:65], v[162:165], v[186:189], v[62:65]
	v_mfma_f32_16x16x32_bf16 v[50:53], v[146:149], v[194:197], v[50:53]
	v_mfma_f32_16x16x32_bf16 v[46:49], v[162:165], v[194:197], v[46:49]
	v_mfma_f32_16x16x32_bf16 v[34:37], v[146:149], v[206:209], v[34:37]
	v_mfma_f32_16x16x32_bf16 v[30:33], v[162:165], v[206:209], v[30:33]
	v_mfma_f32_16x16x32_bf16 v[18:21], v[146:149], v[214:217], v[18:21]
	v_mfma_f32_16x16x32_bf16 v[10:13], v[162:165], v[214:217], v[10:13]
	s_setprio 0
	s_setprio 1
	v_mfma_f32_16x16x32_bf16 v[58:61], v[166:169], v[182:185], v[58:61]
	v_mfma_f32_16x16x32_bf16 v[54:57], v[174:177], v[182:185], v[54:57]
	v_mfma_f32_16x16x32_bf16 v[42:45], v[166:169], v[190:193], v[42:45]
	v_mfma_f32_16x16x32_bf16 v[38:41], v[174:177], v[190:193], v[38:41]
	v_mfma_f32_16x16x32_bf16 v[26:29], v[166:169], v[198:201], v[26:29]
	v_mfma_f32_16x16x32_bf16 v[22:25], v[174:177], v[198:201], v[22:25]
	v_mfma_f32_16x16x32_bf16 v[6:9], v[166:169], v[210:213], v[6:9]
	v_mfma_f32_16x16x32_bf16 v[2:5], v[174:177], v[210:213], v[2:5]
	v_mfma_f32_16x16x32_bf16 v[58:61], v[170:173], v[186:189], v[58:61]
	v_mfma_f32_16x16x32_bf16 v[54:57], v[178:181], v[186:189], v[54:57]
	v_mfma_f32_16x16x32_bf16 v[42:45], v[170:173], v[194:197], v[42:45]
	v_mfma_f32_16x16x32_bf16 v[38:41], v[178:181], v[194:197], v[38:41]
	v_mfma_f32_16x16x32_bf16 v[26:29], v[170:173], v[206:209], v[26:29]
	v_mfma_f32_16x16x32_bf16 v[22:25], v[178:181], v[206:209], v[22:25]
	v_mfma_f32_16x16x32_bf16 v[6:9], v[170:173], v[214:217], v[6:9]
	v_mfma_f32_16x16x32_bf16 v[2:5], v[178:181], v[214:217], v[2:5]
	s_setprio 0
	s_barrier
	s_add_i32 s33, 0, 0x18000
	v_add_u32_e32 v161, s33, v155
	s_add_i32 s57, 0, 0x1c000
	ds_read_b128 v[142:145], v161
	ds_read_b128 v[146:149], v161 offset:1024
	ds_read_b128 v[150:153], v161 offset:2048
	ds_read_b128 v[162:165], v161 offset:3072
	v_add_u32_e32 v161, s57, v155
	ds_read_b128 v[166:169], v161
	ds_read_b128 v[170:173], v161 offset:1024
	ds_read_b128 v[174:177], v161 offset:2048
	ds_read_b128 v[178:181], v161 offset:3072
	s_add_u32 s30, s30, 0x80000
	s_addc_u32 s31, s31, 0
	s_mov_b32 m0, s44
	v_lshl_add_u64 v[224:225], s[30:31], 0, v[136:137]
	ds_read_b128 v[182:185], v160 offset:32768
	ds_read_b128 v[186:189], v160 offset:33792
	ds_read_b128 v[190:193], v160 offset:34816
	ds_read_b128 v[194:197], v160 offset:35840
	ds_read_b128 v[198:201], v160 offset:36864
	ds_read_b128 v[206:209], v160 offset:37888
	ds_read_b128 v[210:213], v160 offset:38912
	ds_read_b128 v[214:217], v160 offset:39936
	global_load_lds_dwordx4 v136, s[30:31]
	v_lshl_add_u64 v[224:225], s[30:31], 0, v[134:135]
	s_mov_b32 m0, s45
	s_nop 0
	global_load_lds_dwordx4 v134, s[30:31]
	s_waitcnt vmcnt(8)
	s_waitcnt lgkmcnt(0)
	s_barrier
	s_setprio 1
	s_waitcnt lgkmcnt(0)
	v_mfma_f32_16x16x32_bf16 v[130:133], v[142:145], v[182:185], v[130:133]
	v_mfma_f32_16x16x32_bf16 v[126:129], v[150:153], v[182:185], v[126:129]
	v_mfma_f32_16x16x32_bf16 v[114:117], v[142:145], v[190:193], v[114:117]
	v_mfma_f32_16x16x32_bf16 v[110:113], v[150:153], v[190:193], v[110:113]
	v_mfma_f32_16x16x32_bf16 v[98:101], v[142:145], v[198:201], v[98:101]
	v_mfma_f32_16x16x32_bf16 v[94:97], v[150:153], v[198:201], v[94:97]
	v_mfma_f32_16x16x32_bf16 v[82:85], v[142:145], v[210:213], v[82:85]
	v_mfma_f32_16x16x32_bf16 v[78:81], v[150:153], v[210:213], v[78:81]
	v_mfma_f32_16x16x32_bf16 v[130:133], v[146:149], v[186:189], v[130:133]
	v_mfma_f32_16x16x32_bf16 v[126:129], v[162:165], v[186:189], v[126:129]
	v_mfma_f32_16x16x32_bf16 v[114:117], v[146:149], v[194:197], v[114:117]
	v_mfma_f32_16x16x32_bf16 v[110:113], v[162:165], v[194:197], v[110:113]
	v_mfma_f32_16x16x32_bf16 v[98:101], v[146:149], v[206:209], v[98:101]
	v_mfma_f32_16x16x32_bf16 v[94:97], v[162:165], v[206:209], v[94:97]
	v_mfma_f32_16x16x32_bf16 v[82:85], v[146:149], v[214:217], v[82:85]
	v_mfma_f32_16x16x32_bf16 v[78:81], v[162:165], v[214:217], v[78:81]
	s_setprio 0
	s_setprio 1
	v_mfma_f32_16x16x32_bf16 v[122:125], v[166:169], v[182:185], v[122:125]
	v_mfma_f32_16x16x32_bf16 v[118:121], v[174:177], v[182:185], v[118:121]
	v_mfma_f32_16x16x32_bf16 v[106:109], v[166:169], v[190:193], v[106:109]
	v_mfma_f32_16x16x32_bf16 v[102:105], v[174:177], v[190:193], v[102:105]
	v_mfma_f32_16x16x32_bf16 v[90:93], v[166:169], v[198:201], v[90:93]
	v_mfma_f32_16x16x32_bf16 v[86:89], v[174:177], v[198:201], v[86:89]
	v_mfma_f32_16x16x32_bf16 v[74:77], v[166:169], v[210:213], v[74:77]
	v_mfma_f32_16x16x32_bf16 v[70:73], v[174:177], v[210:213], v[70:73]
	v_mfma_f32_16x16x32_bf16 v[122:125], v[170:173], v[186:189], v[122:125]
	v_mfma_f32_16x16x32_bf16 v[118:121], v[178:181], v[186:189], v[118:121]
	v_mfma_f32_16x16x32_bf16 v[106:109], v[170:173], v[194:197], v[106:109]
	v_mfma_f32_16x16x32_bf16 v[102:105], v[178:181], v[194:197], v[102:105]
	v_mfma_f32_16x16x32_bf16 v[90:93], v[170:173], v[206:209], v[90:93]
	v_mfma_f32_16x16x32_bf16 v[86:89], v[178:181], v[206:209], v[86:89]
	v_mfma_f32_16x16x32_bf16 v[74:77], v[170:173], v[214:217], v[74:77]
	v_mfma_f32_16x16x32_bf16 v[70:73], v[178:181], v[214:217], v[70:73]
	s_setprio 0
	s_barrier
; #define PG8_STAGE(bufoff, gbase, voff) do { _Pragma("unroll") for (int _i = 0; _i < 2; ++_i) \
;         __builtin_amdgcn_global_load_lds((const unsigned*)((const char*)(gbase) + (voff)[_i]), (PG8_LAS unsigned*)(lds + (bufoff) + ldsw + _i * 8192), 16, 0, 0); } while (0)
; #define PG8_LDA(dst, b, h) do { _Pragma("unroll") for (int m = 0; m < 4; ++m) _Pragma("unroll") for (int k = 0; k < 2; ++k) dst[m][k] = *(const PG8_LAS bf16x8*)(lds + PG8_SA(b, h) + aoff + m * 2048 + k * 1024); } while (0)
; #define PG8_MMA(ai, bj, At, Bt) do { __builtin_amdgcn_s_setprio(1); _Pragma("unroll") for (int m = 0; m < 4; ++m) _Pragma("unroll") for (int n = 0; n < 2; ++n) _Pragma("unroll") for (int k = 0; k < 2; ++k) \
;         acc[ai][bj][m][n] = __builtin_amdgcn_mfma_f32_16x16x32_bf16(Bt[n][k], At[m][k], acc[ai][bj][m][n], 0, 0, 0); __builtin_amdgcn_s_setprio(0); } while (0)
; #define PG8_WAIT_V(n) asm volatile("s_waitcnt vmcnt(" #n ")" ::: "memory")
; #define PG8_WAIT_L(n) asm volatile("s_waitcnt lgkmcnt(" #n ")" ::: "memory")
; #define PG8_BAR __builtin_amdgcn_s_barrier()
; #define PG8_SCHED __builtin_amdgcn_sched_barrier(0)
; template <class Epi, class Sched, bool ALIGN_EPI = false, bool SP2 = false>
; __device__ __forceinline__ void gemm_phase(PG8_LAS unsigned char* lds, const Gemm g, const Sched& S, const Epi& E) {
;     ...
;             PG8_LDA(At, 1, 1); PG8_STAGE(PG8_SB(1, 0), b3, voffB); PG8_STAGE(PG8_SB(1, 1), b3 + hstep, voffB); PG8_STAGE(PG8_SA(1, 0), a3, voffA);
;             PG8_WAIT_V(8); PG8_WAIT_L(0); PG8_BAR; PG8_MMA(1, 0, At, B0); PG8_MMA(1, 1, At, B1); PG8_BAR; PG8_SCHED;
;     ...
;         if constexpr (ALIGN_EPI) { if (wr == 0) PG8_BAR; }
	s_add_i32 s30, s33, s40
	v_lshl_add_u64 v[202:203], v[202:203], 0, s[92:93]
	s_mov_b32 m0, s30
	ds_read_b128 v[182:185], v160 offset:49152
	ds_read_b128 v[186:189], v160 offset:50176
	ds_read_b128 v[190:193], v160 offset:51200
	ds_read_b128 v[194:197], v160 offset:52224
	ds_read_b128 v[198:201], v160 offset:53248
	ds_read_b128 v[206:209], v160 offset:54272
	ds_read_b128 v[210:213], v160 offset:55296
	ds_read_b128 v[214:217], v160 offset:56320
	global_load_lds_dwordx4 v[202:203], off
	s_add_i32 m0, s30, 0x2000
	s_add_u32 s28, s28, 0x80080
	v_lshl_add_u64 v[202:203], v[218:219], 0, s[92:93]
	s_addc_u32 s29, s29, 0
	s_add_i32 s30, s57, s40
	global_load_lds_dwordx4 v[202:203], off
	v_lshl_add_u64 v[202:203], s[28:29], 0, v[0:1]
	s_mov_b32 m0, s30
	s_nop 0
	global_load_lds_dwordx4 v0, s[28:29]
	v_lshl_add_u64 v[202:203], s[28:29], 0, v[14:15]
	s_add_i32 m0, s30, 0x2000
	s_nop 0
	global_load_lds_dwordx4 v14, s[28:29]
	v_lshl_add_u64 v[202:203], v[220:221], 0, s[92:93]
	s_mov_b32 m0, s47
	s_nop 0
	global_load_lds_dwordx4 v[202:203], off
	v_lshl_add_u64 v[202:203], v[222:223], 0, s[92:93]
	s_mov_b32 m0, s48
	s_nop 0
	global_load_lds_dwordx4 v[202:203], off
	s_waitcnt vmcnt(8)
	s_waitcnt lgkmcnt(0)
	s_barrier
	s_setprio 1
	s_waitcnt lgkmcnt(0)
	v_mfma_f32_16x16x32_bf16 v[66:69], v[142:145], v[182:185], v[66:69]
	v_mfma_f32_16x16x32_bf16 v[62:65], v[150:153], v[182:185], v[62:65]
	v_mfma_f32_16x16x32_bf16 v[50:53], v[142:145], v[190:193], v[50:53]
	v_mfma_f32_16x16x32_bf16 v[46:49], v[150:153], v[190:193], v[46:49]
	v_mfma_f32_16x16x32_bf16 v[34:37], v[142:145], v[198:201], v[34:37]
	v_mfma_f32_16x16x32_bf16 v[30:33], v[150:153], v[198:201], v[30:33]
	v_mfma_f32_16x16x32_bf16 v[18:21], v[142:145], v[210:213], v[18:21]
	v_mfma_f32_16x16x32_bf16 v[10:13], v[150:153], v[210:213], v[10:13]
	v_mfma_f32_16x16x32_bf16 v[66:69], v[146:149], v[186:189], v[66:69]
	v_mfma_f32_16x16x32_bf16 v[62:65], v[162:165], v[186:189], v[62:65]
	v_mfma_f32_16x16x32_bf16 v[50:53], v[146:149], v[194:197], v[50:53]
	v_mfma_f32_16x16x32_bf16 v[46:49], v[162:165], v[194:197], v[46:49]
	v_mfma_f32_16x16x32_bf16 v[34:37], v[146:149], v[206:209], v[34:37]
	v_mfma_f32_16x16x32_bf16 v[30:33], v[162:165], v[206:209], v[30:33]
	v_mfma_f32_16x16x32_bf16 v[18:21], v[146:149], v[214:217], v[18:21]
	v_mfma_f32_16x16x32_bf16 v[10:13], v[162:165], v[214:217], v[10:13]
	s_setprio 0
	s_setprio 1
	v_mfma_f32_16x16x32_bf16 v[58:61], v[166:169], v[182:185], v[58:61]
	v_mfma_f32_16x16x32_bf16 v[54:57], v[174:177], v[182:185], v[54:57]
	v_mfma_f32_16x16x32_bf16 v[42:45], v[166:169], v[190:193], v[42:45]
	v_mfma_f32_16x16x32_bf16 v[38:41], v[174:177], v[190:193], v[38:41]
	v_mfma_f32_16x16x32_bf16 v[26:29], v[166:169], v[198:201], v[26:29]
	v_mfma_f32_16x16x32_bf16 v[22:25], v[174:177], v[198:201], v[22:25]
	v_mfma_f32_16x16x32_bf16 v[6:9], v[166:169], v[210:213], v[6:9]
	v_mfma_f32_16x16x32_bf16 v[2:5], v[174:177], v[210:213], v[2:5]
	v_mfma_f32_16x16x32_bf16 v[58:61], v[170:173], v[186:189], v[58:61]
	v_mfma_f32_16x16x32_bf16 v[54:57], v[178:181], v[186:189], v[54:57]
	v_mfma_f32_16x16x32_bf16 v[42:45], v[170:173], v[194:197], v[42:45]
	v_mfma_f32_16x16x32_bf16 v[38:41], v[178:181], v[194:197], v[38:41]
	v_mfma_f32_16x16x32_bf16 v[26:29], v[170:173], v[206:209], v[26:29]
	v_mfma_f32_16x16x32_bf16 v[22:25], v[178:181], v[206:209], v[22:25]
	v_mfma_f32_16x16x32_bf16 v[6:9], v[170:173], v[214:217], v[6:9]
	v_mfma_f32_16x16x32_bf16 v[2:5], v[178:181], v[214:217], v[2:5]
	s_setprio 0
	s_barrier
	s_add_i32 s56, s56, 2
	s_add_u32 s54, s54, 0x100
	s_addc_u32 s55, s55, 0
	s_add_u32 s26, s26, 0x100
	s_addc_u32 s27, s27, 0
	s_cmp_gt_u32 s56, 29
	s_cbranch_scc0 .LBB0_1223
	s_and_b64 vcc, exec, s[14:15]
	s_cbranch_vccz .LBB0_1226
	s_barrier

; #define PG8_STAGE(bufoff, gbase, voff) do { _Pragma("unroll") for (int _i = 0; _i < 2; ++_i) \
;         __builtin_amdgcn_global_load_lds((const unsigned*)((const char*)(gbase) + (voff)[_i]), (PG8_LAS unsigned*)(lds + (bufoff) + ldsw + _i * 8192), 16, 0, 0); } while (0)
; #define PG8_LDA(dst, b, h) do { _Pragma("unroll") for (int m = 0; m < 4; ++m) _Pragma("unroll") for (int k = 0; k < 2; ++k) dst[m][k] = *(const PG8_LAS bf16x8*)(lds + PG8_SA(b, h) + aoff + m * 2048 + k * 1024); } while (0)
; #define PG8_LDB(dst, b, h) do { _Pragma("unroll") for (int n = 0; n < 2; ++n) _Pragma("unroll") for (int k = 0; k < 2; ++k) dst[n][k] = *(const PG8_LAS bf16x8*)(lds + PG8_SB(b, h) + boff + n * 2048 + k * 1024); } while (0)
; #define PG8_MMA(ai, bj, At, Bt) do { __builtin_amdgcn_s_setprio(1); _Pragma("unroll") for (int m = 0; m < 4; ++m) _Pragma("unroll") for (int n = 0; n < 2; ++n) _Pragma("unroll") for (int k = 0; k < 2; ++k) \
;         acc[ai][bj][m][n] = __builtin_amdgcn_mfma_f32_16x16x32_bf16(Bt[n][k], At[m][k], acc[ai][bj][m][n], 0, 0, 0); __builtin_amdgcn_s_setprio(0); } while (0)
; #define PG8_WAIT_V(n) asm volatile("s_waitcnt vmcnt(" #n ")" ::: "memory")
; #define PG8_WAIT_L(n) asm volatile("s_waitcnt lgkmcnt(" #n ")" ::: "memory")
; template <class Epi, class Sched, bool ALIGN_EPI = false, bool SP2 = false>
; __device__ __forceinline__ void gemm_phase(PG8_LAS unsigned char* lds, const Gemm g, const Sched& S, const Epi& E) {
;     ...
;         for (int t = 0; t < nt; t += 2) {
;             const bool last = (t == nt - 2);
;             const char* a1 = cA + (size_t)(t + 1) * kstep;
;             const char* a2 = last ? nA : cA + (size_t)(t + 2) * kstep; const char* b2 = last ? nB : cB + (size_t)(t + 2) * kstep;
;             const char* a3 = a2 + kstep; const char* b3 = b2 + kstep;
;             if (last && has_next) S.a_ready(nxt);
;             if constexpr (Epi::MID) { if (t == nt / 2) E.mid(acc, cur, wr, wc, fr, fq); }
;             if constexpr (SP2) {
;             PG8_LDB(B0, 0, 0); PG8_LDB(B1, 0, 1); PG8_SCHED; PG8_LDA(At, 0, 0); PG8_STAGE(PG8_SA(1, 1), a1 + hstep, voffA);
;             PG8_WAIT_V(8); PG8_WAIT_L(0); PG8_BAR; PG8_MMA(0, 0, At, B0); PG8_MMA(0, 1, At, B1); PG8_BAR; PG8_SCHED;
;             PG8_LDA(At, 0, 1); PG8_STAGE(PG8_SB(0, 0), b2, voffB); PG8_STAGE(PG8_SB(0, 1), b2 + hstep, voffB); PG8_STAGE(PG8_SA(0, 0), a2, voffA);
.LBB0_1329:
	s_add_u32 s4, s24, 0x100
	s_addc_u32 s5, s25, 0
	s_add_i32 s33, 0, 0x10000
	s_cmpk_eq_i32 s53, 0x54
	s_cselect_b32 s29, s21, s5
	s_cselect_b32 s28, s20, s4
	s_cselect_b32 s27, s23, s52
	s_cselect_b32 s26, s22, s51
	s_add_i32 s54, 0, 0x14000
	v_add_u32_e32 v98, s33, v199
	v_add_u32_e32 v146, s54, v199
	ds_read_b128 v[70:73], v98
	ds_read_b128 v[74:77], v98 offset:1024
	ds_read_b128 v[86:89], v98 offset:2048
	ds_read_b128 v[98:101], v98 offset:3072
	ds_read_b128 v[110:113], v146
	ds_read_b128 v[122:125], v146 offset:1024
	ds_read_b128 v[134:137], v146 offset:2048
	ds_read_b128 v[146:149], v146 offset:3072
	v_lshl_add_u64 v[202:203], s[24:25], 0, v[208:209]
	s_add_i32 m0, s39, 0xc000
	ds_read_b128 v[158:161], v201
	ds_read_b128 v[162:165], v201 offset:1024
	ds_read_b128 v[174:177], v201 offset:2048
	ds_read_b128 v[178:181], v201 offset:3072
	ds_read_b128 v[182:185], v201 offset:4096
	ds_read_b128 v[186:189], v201 offset:5120
	ds_read_b128 v[190:193], v201 offset:6144
	ds_read_b128 v[210:213], v201 offset:7168
	global_load_lds_dwordx4 v208, s[24:25]
	v_lshl_add_u64 v[202:203], s[24:25], 0, v[206:207]
	s_add_i32 m0, s39, 0xe000
	s_nop 0
	global_load_lds_dwordx4 v206, s[24:25]
	s_waitcnt vmcnt(8)
	s_waitcnt lgkmcnt(0)
	s_barrier
	s_setprio 1
	s_waitcnt lgkmcnt(0)
	v_mfma_f32_16x16x32_bf16 v[170:173], v[70:73], v[158:161], v[170:173]
	v_mfma_f32_16x16x32_bf16 v[166:169], v[86:89], v[158:161], v[166:169]
	v_mfma_f32_16x16x32_bf16 v[142:145], v[70:73], v[174:177], v[142:145]
	v_mfma_f32_16x16x32_bf16 v[138:141], v[86:89], v[174:177], v[138:141]
	v_mfma_f32_16x16x32_bf16 v[118:121], v[70:73], v[182:185], v[118:121]
	v_mfma_f32_16x16x32_bf16 v[114:117], v[86:89], v[182:185], v[114:117]
	v_mfma_f32_16x16x32_bf16 v[94:97], v[70:73], v[190:193], v[94:97]
	v_mfma_f32_16x16x32_bf16 v[90:93], v[86:89], v[190:193], v[90:93]
	v_mfma_f32_16x16x32_bf16 v[170:173], v[74:77], v[162:165], v[170:173]
	v_mfma_f32_16x16x32_bf16 v[166:169], v[98:101], v[162:165], v[166:169]
	v_mfma_f32_16x16x32_bf16 v[142:145], v[74:77], v[178:181], v[142:145]
	v_mfma_f32_16x16x32_bf16 v[138:141], v[98:101], v[178:181], v[138:141]
	v_mfma_f32_16x16x32_bf16 v[118:121], v[74:77], v[186:189], v[118:121]
	v_mfma_f32_16x16x32_bf16 v[114:117], v[98:101], v[186:189], v[114:117]
	v_mfma_f32_16x16x32_bf16 v[94:97], v[74:77], v[210:213], v[94:97]
	v_mfma_f32_16x16x32_bf16 v[90:93], v[98:101], v[210:213], v[90:93]
	s_setprio 0
	s_setprio 1
	v_mfma_f32_16x16x32_bf16 v[154:157], v[110:113], v[158:161], v[154:157]
	v_mfma_f32_16x16x32_bf16 v[150:153], v[134:137], v[158:161], v[150:153]
	v_mfma_f32_16x16x32_bf16 v[130:133], v[110:113], v[174:177], v[130:133]
	v_mfma_f32_16x16x32_bf16 v[126:129], v[134:137], v[174:177], v[126:129]
	v_mfma_f32_16x16x32_bf16 v[106:109], v[110:113], v[182:185], v[106:109]
	v_mfma_f32_16x16x32_bf16 v[102:105], v[134:137], v[182:185], v[102:105]
	v_mfma_f32_16x16x32_bf16 v[82:85], v[110:113], v[190:193], v[82:85]
	v_mfma_f32_16x16x32_bf16 v[78:81], v[134:137], v[190:193], v[78:81]
	v_mfma_f32_16x16x32_bf16 v[154:157], v[122:125], v[162:165], v[154:157]
	v_mfma_f32_16x16x32_bf16 v[150:153], v[146:149], v[162:165], v[150:153]
	v_mfma_f32_16x16x32_bf16 v[130:133], v[122:125], v[178:181], v[130:133]
	v_mfma_f32_16x16x32_bf16 v[126:129], v[146:149], v[178:181], v[126:129]
	v_mfma_f32_16x16x32_bf16 v[106:109], v[122:125], v[186:189], v[106:109]
	v_mfma_f32_16x16x32_bf16 v[102:105], v[146:149], v[186:189], v[102:105]
	v_mfma_f32_16x16x32_bf16 v[82:85], v[122:125], v[210:213], v[82:85]
	v_mfma_f32_16x16x32_bf16 v[78:81], v[146:149], v[210:213], v[78:81]
	s_setprio 0
	s_barrier
	s_add_i32 s24, s33, s38
	v_lshl_add_u64 v[202:203], s[26:27], 0, v[0:1]
	s_mov_b32 m0, s24
	ds_read_b128 v[158:161], v201 offset:16384
	ds_read_b128 v[162:165], v201 offset:17408
	ds_read_b128 v[174:177], v201 offset:18432
	ds_read_b128 v[178:181], v201 offset:19456
	ds_read_b128 v[182:185], v201 offset:20480
	ds_read_b128 v[186:189], v201 offset:21504
	ds_read_b128 v[190:193], v201 offset:22528
	ds_read_b128 v[210:213], v201 offset:23552
	global_load_lds_dwordx4 v0, s[26:27]
	s_add_i32 m0, s24, 0x2000
	s_add_u32 s24, s26, 0x160000
	v_lshl_add_u64 v[214:215], s[26:27], 0, v[196:197]
	s_addc_u32 s25, s27, 0
	s_add_i32 s33, s54, s38
	global_load_lds_dwordx4 v196, s[26:27]
	v_lshl_add_u64 v[216:217], s[24:25], 0, v[0:1]
	s_mov_b32 m0, s33
	v_lshl_add_u64 v[218:219], s[28:29], 0, v[194:195]
	global_load_lds_dwordx4 v0, s[24:25]
	v_lshl_add_u64 v[216:217], s[24:25], 0, v[196:197]
	s_add_i32 m0, s33, 0x2000
	s_nop 0
	global_load_lds_dwordx4 v196, s[24:25]
	v_lshl_add_u64 v[216:217], s[28:29], 0, v[14:15]
	s_mov_b32 m0, s39
	s_nop 0
	global_load_lds_dwordx4 v14, s[28:29]
	s_mov_b32 m0, s40
	s_nop 0
	global_load_lds_dwordx4 v194, s[28:29]
	s_waitcnt vmcnt(8)
	s_waitcnt lgkmcnt(0)
	s_barrier
; #define PG8_STAGE(bufoff, gbase, voff) do { _Pragma("unroll") for (int _i = 0; _i < 2; ++_i) \
;         __builtin_amdgcn_global_load_lds((const unsigned*)((const char*)(gbase) + (voff)[_i]), (PG8_LAS unsigned*)(lds + (bufoff) + ldsw + _i * 8192), 16, 0, 0); } while (0)
; #define PG8_LDA(dst, b, h) do { _Pragma("unroll") for (int m = 0; m < 4; ++m) _Pragma("unroll") for (int k = 0; k < 2; ++k) dst[m][k] = *(const PG8_LAS bf16x8*)(lds + PG8_SA(b, h) + aoff + m * 2048 + k * 1024); } while (0)
; #define PG8_LDB(dst, b, h) do { _Pragma("unroll") for (int n = 0; n < 2; ++n) _Pragma("unroll") for (int k = 0; k < 2; ++k) dst[n][k] = *(const PG8_LAS bf16x8*)(lds + PG8_SB(b, h) + boff + n * 2048 + k * 1024); } while (0)
; #define PG8_MMA(ai, bj, At, Bt) do { __builtin_amdgcn_s_setprio(1); _Pragma("unroll") for (int m = 0; m < 4; ++m) _Pragma("unroll") for (int n = 0; n < 2; ++n) _Pragma("unroll") for (int k = 0; k < 2; ++k) \
;         acc[ai][bj][m][n] = __builtin_amdgcn_mfma_f32_16x16x32_bf16(Bt[n][k], At[m][k], acc[ai][bj][m][n], 0, 0, 0); __builtin_amdgcn_s_setprio(0); } while (0)
; #define PG8_WAIT_V(n) asm volatile("s_waitcnt vmcnt(" #n ")" ::: "memory")
; #define PG8_WAIT_L(n) asm volatile("s_waitcnt lgkmcnt(" #n ")" ::: "memory")
; #define PG8_BAR __builtin_amdgcn_s_barrier()
; #define PG8_SCHED __builtin_amdgcn_sched_barrier(0)
; template <class Epi, class Sched, bool ALIGN_EPI = false, bool SP2 = false>
; __device__ __forceinline__ void gemm_phase(PG8_LAS unsigned char* lds, const Gemm g, const Sched& S, const Epi& E) {
;     ...
;             PG8_WAIT_V(8); PG8_WAIT_L(0); PG8_BAR; PG8_MMA(1, 0, At, B0); PG8_MMA(1, 1, At, B1); PG8_BAR; PG8_SCHED;
;             PG8_LDB(B0, 1, 0); PG8_LDB(B1, 1, 1); PG8_SCHED; PG8_LDA(At, 1, 0); PG8_STAGE(PG8_SA(0, 1), a2 + hstep, voffA);
;             PG8_WAIT_V(8); PG8_WAIT_L(0); PG8_BAR; PG8_MMA(0, 0, At, B0); PG8_MMA(0, 1, At, B1); PG8_BAR; PG8_SCHED;
	s_setprio 1
	s_waitcnt lgkmcnt(0)
	v_mfma_f32_16x16x32_bf16 v[66:69], v[70:73], v[158:161], v[66:69]
	v_mfma_f32_16x16x32_bf16 v[62:65], v[86:89], v[158:161], v[62:65]
	v_mfma_f32_16x16x32_bf16 v[50:53], v[70:73], v[174:177], v[50:53]
	v_mfma_f32_16x16x32_bf16 v[46:49], v[86:89], v[174:177], v[46:49]
	v_mfma_f32_16x16x32_bf16 v[34:37], v[70:73], v[182:185], v[34:37]
	v_mfma_f32_16x16x32_bf16 v[30:33], v[86:89], v[182:185], v[30:33]
	v_mfma_f32_16x16x32_bf16 v[18:21], v[70:73], v[190:193], v[18:21]
	v_mfma_f32_16x16x32_bf16 v[10:13], v[86:89], v[190:193], v[10:13]
	v_mfma_f32_16x16x32_bf16 v[66:69], v[74:77], v[162:165], v[66:69]
	v_mfma_f32_16x16x32_bf16 v[62:65], v[98:101], v[162:165], v[62:65]
	v_mfma_f32_16x16x32_bf16 v[50:53], v[74:77], v[178:181], v[50:53]
	v_mfma_f32_16x16x32_bf16 v[46:49], v[98:101], v[178:181], v[46:49]
	v_mfma_f32_16x16x32_bf16 v[34:37], v[74:77], v[186:189], v[34:37]
	v_mfma_f32_16x16x32_bf16 v[30:33], v[98:101], v[186:189], v[30:33]
	v_mfma_f32_16x16x32_bf16 v[18:21], v[74:77], v[210:213], v[18:21]
	v_mfma_f32_16x16x32_bf16 v[10:13], v[98:101], v[210:213], v[10:13]
	s_setprio 0
	s_setprio 1
	v_mfma_f32_16x16x32_bf16 v[58:61], v[110:113], v[158:161], v[58:61]
	v_mfma_f32_16x16x32_bf16 v[54:57], v[134:137], v[158:161], v[54:57]
	v_mfma_f32_16x16x32_bf16 v[42:45], v[110:113], v[174:177], v[42:45]
	v_mfma_f32_16x16x32_bf16 v[38:41], v[134:137], v[174:177], v[38:41]
	v_mfma_f32_16x16x32_bf16 v[26:29], v[110:113], v[182:185], v[26:29]
	v_mfma_f32_16x16x32_bf16 v[22:25], v[134:137], v[182:185], v[22:25]
	v_mfma_f32_16x16x32_bf16 v[6:9], v[110:113], v[190:193], v[6:9]
	v_mfma_f32_16x16x32_bf16 v[2:5], v[134:137], v[190:193], v[2:5]
	v_mfma_f32_16x16x32_bf16 v[58:61], v[122:125], v[162:165], v[58:61]
	v_mfma_f32_16x16x32_bf16 v[54:57], v[146:149], v[162:165], v[54:57]
	v_mfma_f32_16x16x32_bf16 v[42:45], v[122:125], v[178:181], v[42:45]
	v_mfma_f32_16x16x32_bf16 v[38:41], v[146:149], v[178:181], v[38:41]
	v_mfma_f32_16x16x32_bf16 v[26:29], v[122:125], v[186:189], v[26:29]
	v_mfma_f32_16x16x32_bf16 v[22:25], v[146:149], v[186:189], v[22:25]
	v_mfma_f32_16x16x32_bf16 v[6:9], v[122:125], v[210:213], v[6:9]
	v_mfma_f32_16x16x32_bf16 v[2:5], v[146:149], v[210:213], v[2:5]
	s_setprio 0
	s_barrier
	s_add_i32 s33, 0, 0x18000
	s_add_i32 s54, 0, 0x1c000
	v_add_u32_e32 v98, s33, v199
	v_add_u32_e32 v146, s54, v199
	ds_read_b128 v[70:73], v98
	ds_read_b128 v[74:77], v98 offset:1024
	ds_read_b128 v[86:89], v98 offset:2048
	ds_read_b128 v[98:101], v98 offset:3072
	ds_read_b128 v[110:113], v146
	ds_read_b128 v[122:125], v146 offset:1024
	ds_read_b128 v[134:137], v146 offset:2048
	ds_read_b128 v[146:149], v146 offset:3072
	s_add_u32 s24, s28, 0x160000
	s_addc_u32 s25, s29, 0
	s_mov_b32 m0, s41
	v_lshl_add_u64 v[220:221], s[24:25], 0, v[14:15]
	ds_read_b128 v[158:161], v201 offset:32768
	ds_read_b128 v[162:165], v201 offset:33792
	ds_read_b128 v[174:177], v201 offset:34816
	ds_read_b128 v[178:181], v201 offset:35840
	ds_read_b128 v[182:185], v201 offset:36864
	ds_read_b128 v[186:189], v201 offset:37888
	ds_read_b128 v[190:193], v201 offset:38912
	ds_read_b128 v[210:213], v201 offset:39936
	global_load_lds_dwordx4 v14, s[24:25]
	v_lshl_add_u64 v[220:221], s[24:25], 0, v[194:195]
	s_mov_b32 m0, s42
	s_nop 0
	global_load_lds_dwordx4 v194, s[24:25]
	s_waitcnt vmcnt(8)
	s_waitcnt lgkmcnt(0)
	s_barrier
	s_setprio 1
	s_waitcnt lgkmcnt(0)
	v_mfma_f32_16x16x32_bf16 v[170:173], v[70:73], v[158:161], v[170:173]
	v_mfma_f32_16x16x32_bf16 v[166:169], v[86:89], v[158:161], v[166:169]
	v_mfma_f32_16x16x32_bf16 v[142:145], v[70:73], v[174:177], v[142:145]
	v_mfma_f32_16x16x32_bf16 v[138:141], v[86:89], v[174:177], v[138:141]
	v_mfma_f32_16x16x32_bf16 v[118:121], v[70:73], v[182:185], v[118:121]
	v_mfma_f32_16x16x32_bf16 v[114:117], v[86:89], v[182:185], v[114:117]
	v_mfma_f32_16x16x32_bf16 v[94:97], v[70:73], v[190:193], v[94:97]
	v_mfma_f32_16x16x32_bf16 v[90:93], v[86:89], v[190:193], v[90:93]
	v_mfma_f32_16x16x32_bf16 v[170:173], v[74:77], v[162:165], v[170:173]
	v_mfma_f32_16x16x32_bf16 v[166:169], v[98:101], v[162:165], v[166:169]
	v_mfma_f32_16x16x32_bf16 v[142:145], v[74:77], v[178:181], v[142:145]
	v_mfma_f32_16x16x32_bf16 v[138:141], v[98:101], v[178:181], v[138:141]
	v_mfma_f32_16x16x32_bf16 v[118:121], v[74:77], v[186:189], v[118:121]
	v_mfma_f32_16x16x32_bf16 v[114:117], v[98:101], v[186:189], v[114:117]
	v_mfma_f32_16x16x32_bf16 v[94:97], v[74:77], v[210:213], v[94:97]
	v_mfma_f32_16x16x32_bf16 v[90:93], v[98:101], v[210:213], v[90:93]
	s_setprio 0
	s_setprio 1
	v_mfma_f32_16x16x32_bf16 v[154:157], v[110:113], v[158:161], v[154:157]
	v_mfma_f32_16x16x32_bf16 v[150:153], v[134:137], v[158:161], v[150:153]
	v_mfma_f32_16x16x32_bf16 v[130:133], v[110:113], v[174:177], v[130:133]
	v_mfma_f32_16x16x32_bf16 v[126:129], v[134:137], v[174:177], v[126:129]
	v_mfma_f32_16x16x32_bf16 v[106:109], v[110:113], v[182:185], v[106:109]
	v_mfma_f32_16x16x32_bf16 v[102:105], v[134:137], v[182:185], v[102:105]
	v_mfma_f32_16x16x32_bf16 v[82:85], v[110:113], v[190:193], v[82:85]
	v_mfma_f32_16x16x32_bf16 v[78:81], v[134:137], v[190:193], v[78:81]
	v_mfma_f32_16x16x32_bf16 v[154:157], v[122:125], v[162:165], v[154:157]
	v_mfma_f32_16x16x32_bf16 v[150:153], v[146:149], v[162:165], v[150:153]
	v_mfma_f32_16x16x32_bf16 v[130:133], v[122:125], v[178:181], v[130:133]
	v_mfma_f32_16x16x32_bf16 v[126:129], v[146:149], v[178:181], v[126:129]
	v_mfma_f32_16x16x32_bf16 v[106:109], v[122:125], v[186:189], v[106:109]
	v_mfma_f32_16x16x32_bf16 v[102:105], v[146:149], v[186:189], v[102:105]
	v_mfma_f32_16x16x32_bf16 v[82:85], v[122:125], v[210:213], v[82:85]
	v_mfma_f32_16x16x32_bf16 v[78:81], v[146:149], v[210:213], v[78:81]
	s_setprio 0
	s_barrier
; #define PG8_STAGE(bufoff, gbase, voff) do { _Pragma("unroll") for (int _i = 0; _i < 2; ++_i) \
;         __builtin_amdgcn_global_load_lds((const unsigned*)((const char*)(gbase) + (voff)[_i]), (PG8_LAS unsigned*)(lds + (bufoff) + ldsw + _i * 8192), 16, 0, 0); } while (0)
; #define PG8_LDA(dst, b, h) do { _Pragma("unroll") for (int m = 0; m < 4; ++m) _Pragma("unroll") for (int k = 0; k < 2; ++k) dst[m][k] = *(const PG8_LAS bf16x8*)(lds + PG8_SA(b, h) + aoff + m * 2048 + k * 1024); } while (0)
; #define PG8_MMA(ai, bj, At, Bt) do { __builtin_amdgcn_s_setprio(1); _Pragma("unroll") for (int m = 0; m < 4; ++m) _Pragma("unroll") for (int n = 0; n < 2; ++n) _Pragma("unroll") for (int k = 0; k < 2; ++k) \
;         acc[ai][bj][m][n] = __builtin_amdgcn_mfma_f32_16x16x32_bf16(Bt[n][k], At[m][k], acc[ai][bj][m][n], 0, 0, 0); __builtin_amdgcn_s_setprio(0); } while (0)
; #define PG8_WAIT_V(n) asm volatile("s_waitcnt vmcnt(" #n ")" ::: "memory")
; #define PG8_WAIT_L(n) asm volatile("s_waitcnt lgkmcnt(" #n ")" ::: "memory")
; #define PG8_BAR __builtin_amdgcn_s_barrier()
; #define PG8_SCHED __builtin_amdgcn_sched_barrier(0)
; template <class Epi, class Sched, bool ALIGN_EPI = false, bool SP2 = false>
; __device__ __forceinline__ void gemm_phase(PG8_LAS unsigned char* lds, const Gemm g, const Sched& S, const Epi& E) {
;     ...
;             PG8_LDA(At, 1, 1); PG8_STAGE(PG8_SB(1, 0), b3, voffB); PG8_STAGE(PG8_SB(1, 1), b3 + hstep, voffB); PG8_STAGE(PG8_SA(1, 0), a3, voffA);
;             PG8_WAIT_V(8); PG8_WAIT_L(0); PG8_BAR; PG8_MMA(1, 0, At, B0); PG8_MMA(1, 1, At, B1); PG8_BAR; PG8_SCHED;
;     ...
;         if constexpr (ALIGN_EPI) { if (wr == 0) PG8_BAR; }
	s_add_i32 s24, s33, s38
	v_lshl_add_u64 v[202:203], v[202:203], 0, s[92:93]
	s_mov_b32 m0, s24
	ds_read_b128 v[158:161], v201 offset:49152
	ds_read_b128 v[162:165], v201 offset:50176
	ds_read_b128 v[174:177], v201 offset:51200
	ds_read_b128 v[178:181], v201 offset:52224
	ds_read_b128 v[182:185], v201 offset:53248
	ds_read_b128 v[186:189], v201 offset:54272
	ds_read_b128 v[190:193], v201 offset:55296
	ds_read_b128 v[210:213], v201 offset:56320
	global_load_lds_dwordx4 v[202:203], off
	s_add_i32 m0, s24, 0x2000
	s_add_u32 s24, s26, 0x160080
	v_lshl_add_u64 v[202:203], v[214:215], 0, s[92:93]
	s_addc_u32 s25, s27, 0
	s_add_i32 s26, s54, s38
	global_load_lds_dwordx4 v[202:203], off
	v_lshl_add_u64 v[202:203], s[24:25], 0, v[0:1]
	s_mov_b32 m0, s26
	s_nop 0
	global_load_lds_dwordx4 v0, s[24:25]
	v_lshl_add_u64 v[202:203], s[24:25], 0, v[196:197]
	s_add_i32 m0, s26, 0x2000
	s_nop 0
	global_load_lds_dwordx4 v196, s[24:25]
	v_lshl_add_u64 v[202:203], v[216:217], 0, s[92:93]
	s_mov_b32 m0, s44
	s_nop 0
	global_load_lds_dwordx4 v[202:203], off
	v_lshl_add_u64 v[202:203], v[218:219], 0, s[92:93]
	s_mov_b32 m0, s45
	s_nop 0
	global_load_lds_dwordx4 v[202:203], off
	s_waitcnt vmcnt(8)
	s_waitcnt lgkmcnt(0)
	s_barrier
	s_setprio 1
	s_waitcnt lgkmcnt(0)
	v_mfma_f32_16x16x32_bf16 v[66:69], v[70:73], v[158:161], v[66:69]
	v_mfma_f32_16x16x32_bf16 v[62:65], v[86:89], v[158:161], v[62:65]
	v_mfma_f32_16x16x32_bf16 v[50:53], v[70:73], v[174:177], v[50:53]
	v_mfma_f32_16x16x32_bf16 v[46:49], v[86:89], v[174:177], v[46:49]
	v_mfma_f32_16x16x32_bf16 v[34:37], v[70:73], v[182:185], v[34:37]
	v_mfma_f32_16x16x32_bf16 v[30:33], v[86:89], v[182:185], v[30:33]
	v_mfma_f32_16x16x32_bf16 v[18:21], v[70:73], v[190:193], v[18:21]
	v_mfma_f32_16x16x32_bf16 v[10:13], v[86:89], v[190:193], v[10:13]
	v_mfma_f32_16x16x32_bf16 v[66:69], v[74:77], v[162:165], v[66:69]
	v_mfma_f32_16x16x32_bf16 v[62:65], v[98:101], v[162:165], v[62:65]
	v_mfma_f32_16x16x32_bf16 v[50:53], v[74:77], v[178:181], v[50:53]
	v_mfma_f32_16x16x32_bf16 v[46:49], v[98:101], v[178:181], v[46:49]
	v_mfma_f32_16x16x32_bf16 v[34:37], v[74:77], v[186:189], v[34:37]
	v_mfma_f32_16x16x32_bf16 v[30:33], v[98:101], v[186:189], v[30:33]
	v_mfma_f32_16x16x32_bf16 v[18:21], v[74:77], v[210:213], v[18:21]
	v_mfma_f32_16x16x32_bf16 v[10:13], v[98:101], v[210:213], v[10:13]
	s_setprio 0
	s_setprio 1
	v_mfma_f32_16x16x32_bf16 v[58:61], v[110:113], v[158:161], v[58:61]
	v_mfma_f32_16x16x32_bf16 v[54:57], v[134:137], v[158:161], v[54:57]
	v_mfma_f32_16x16x32_bf16 v[42:45], v[110:113], v[174:177], v[42:45]
	v_mfma_f32_16x16x32_bf16 v[38:41], v[134:137], v[174:177], v[38:41]
	v_mfma_f32_16x16x32_bf16 v[26:29], v[110:113], v[182:185], v[26:29]
	v_mfma_f32_16x16x32_bf16 v[22:25], v[134:137], v[182:185], v[22:25]
	v_mfma_f32_16x16x32_bf16 v[6:9], v[110:113], v[190:193], v[6:9]
	v_mfma_f32_16x16x32_bf16 v[2:5], v[134:137], v[190:193], v[2:5]
	v_mfma_f32_16x16x32_bf16 v[58:61], v[122:125], v[162:165], v[58:61]
	v_mfma_f32_16x16x32_bf16 v[54:57], v[146:149], v[162:165], v[54:57]
	v_mfma_f32_16x16x32_bf16 v[42:45], v[122:125], v[178:181], v[42:45]
	v_mfma_f32_16x16x32_bf16 v[38:41], v[146:149], v[178:181], v[38:41]
	v_mfma_f32_16x16x32_bf16 v[26:29], v[122:125], v[186:189], v[26:29]
	v_mfma_f32_16x16x32_bf16 v[22:25], v[146:149], v[186:189], v[22:25]
	v_mfma_f32_16x16x32_bf16 v[6:9], v[122:125], v[210:213], v[6:9]
	v_mfma_f32_16x16x32_bf16 v[2:5], v[146:149], v[210:213], v[2:5]
	s_setprio 0
	s_barrier
	s_add_i32 s53, s53, 2
	s_add_u32 s51, s51, 0x100
	s_addc_u32 s52, s52, 0
	s_cmpk_gt_u32 s53, 0x55
	s_mov_b64 s[24:25], s[4:5]
	s_cbranch_scc0 .LBB0_1329
	s_and_b64 vcc, exec, s[16:17]
	s_cbranch_vccz .LBB0_1332
	s_barrier
